# attention: the next unit's Q rows and K/V tiles 0,1 are prefetched (into registers / LDS slots 0,1) while the current unit's epilogue runs in LDS slots 2,3; second-unit prologue skips those loads and
# speedup vs baseline: 1.0034x; 1.0034x over previous
; #define LAS __attribute__((address_space(3)))
; __device__ __forceinline__ void attn_unit(unsigned char* ws, const float* sub_g, LAS unsigned char* lds, int h, int qb, float negM, float lam) {
;     const int tid = threadIdx.x, lane = tid & 63, r32 = lane & 31, hi = lane >> 5;
;     const int wid = __builtin_amdgcn_readfirstlane(tid >> 6), map = wid >> 2, wq = wid & 3;
;     const int qrow0 = qb * 128 + 32 * wq;
;     const bf16_t* Qp = (const bf16_t*)(ws + WS_Q); const bf16_t* Kp = (const bf16_t*)(ws + WS_K); const bf16_t* VTp = (const bf16_t*)(ws + WS_VT);
;     bf16x8 qf[4];
;     {
;         const bf16_t* qp = Qp + (size_t)(qrow0 + r32) * 1024 + (h * 2 + map) * 64 + 8 * hi;
; #pragma unroll
;         for (int d0 = 0; d0 < 4; ++d0) qf[d0] = *(const bf16x8*)(qp + 16 * d0);
;     }
;     const bf16_t* kg[2]; const bf16_t* vg[2];
; #pragma unroll
;     for (int i = 0; i < 2; ++i) {
;         const int g = 2 * wid + i;
;         const int kr = 4 * g + (lane >> 4), kc = (lane & 15) ^ (kr & 15);
;         kg[i] = Kp + (size_t)kr * 1024 + h * 128 + kc * 8;
;         const int vr = 8 * g + (lane >> 3), vc = (lane & 7) ^ ((vr >> 1) & 7);
;         vg[i] = VTp + (size_t)(h * 128 + vr) * NTOK + vc * 8;
;     }
;     const unsigned dmaoff = (unsigned)wid * 2048u;
;     ...
;     int kad[4], vad[4];
; #pragma unroll
;     for (int d0 = 0; d0 < 4; ++d0) kad[d0] = r32 * 256 + (((map * 8 + 2 * d0 + hi) ^ (r32 & 15)) << 4);
; #pragma unroll
;     for (int j = 0; j < 4; ++j) vad[j] = AT_KBYTES + r32 * 128 + (((2 * j + hi) ^ ((r32 >> 1) & 7)) << 4);
;     ...
;     f32x16 o[4];
; #pragma unroll
;     for (int b = 0; b < 4; ++b)
; #pragma unroll
;         for (int r = 0; r < 16; ++r) o[b][r] = 0.f;
;     f32x16 negm;
; #pragma unroll
;     for (int r = 0; r < 16; ++r) negm[r] = negM;
;     float l0 = 0.f, l1 = 0.f;
;     AT_DMA(0); AT_ADV();
;     asm volatile("s_waitcnt vmcnt(0)" ::: "memory");
;     __builtin_amdgcn_s_barrier();
;     AT_DMA(AT_BUF); AT_ADV();
;     f32x16 pa, pb;
;     {
;         f32x16 s0 = negm, s1 = negm;
; #pragma unroll
;         for (int d0 = 0; d0 < 4; ++d0) { s0 = __builtin_amdgcn_mfma_f32_32x32x16_bf16(KFR(0, d0, 0), qf[d0], s0, 0, 0, 0); s1 = __builtin_amdgcn_mfma_f32_32x32x16_bf16(KFR(0, d0, 1), qf[d0], s1, 0, 0, 0); }
; #pragma unroll
;         for (int r = 0; r < 16; ++r) { pa[r] = __builtin_amdgcn_exp2f(s0[r]); pb[r] = __builtin_amdgcn_exp2f(s1[r]); }
.LBB0_830:
	s_cmpk_gt_i32 s20, 0xff
	s_cbranch_scc1 .Lpro_b
	v_readfirstlane_b32 s25, v220
	s_bfe_u32 s29, s25, 0x20006
	s_lshl_b32 s8, s20, 4
	s_and_b32 s8, s8, 0xffffff80
	s_lshl_b32 s21, s29, 5
	s_or_b32 s21, s21, s8
	s_lshr_b32 s28, s25, 8
	v_or_b32_e32 v16, s21, v153
	s_lshl_b32 s8, s20, 7
	v_ashrrev_i32_e32 v17, 31, v16
	s_and_b32 s24, s8, 0x380
	s_lshl_b32 s8, s28, 6
	v_lshlrev_b64 v[16:17], 11, v[16:17]
	s_add_i32 s8, s8, s24
	v_lshl_add_u64 v[16:17], s[4:5], 0, v[16:17]
	s_lshl_b32 s8, s8, 1
	v_lshl_add_u64 v[16:17], v[16:17], 0, s[8:9]
	v_lshlrev_b32_e32 v130, 4, v150
	s_mov_b64 s[34:35], 0x8000
	v_lshl_add_u64 v[16:17], v[16:17], 0, v[130:131]
	v_lshl_add_u64 v[18:19], v[16:17], 0, s[34:35]
	global_load_dwordx4 v[112:115], v[16:17], off
	global_load_dwordx4 v[116:119], v[16:17], off offset:64
	global_load_dwordx4 v[120:123], v[18:19], off
	global_load_dwordx4 v[124:127], v[18:19], off offset:64
	s_lshr_b32 s33, s25, 6
	s_lshr_b32 s8, s25, 5
	s_lshl_b32 s30, s24, 1
	s_add_u32 s30, s3, s30
	s_addc_u32 s31, s18, 0
	s_lshl_b32 s34, s33, 3
	s_bfe_u32 s98, s25, 0x10007
	s_lshl_b32 s98, s98, 3
	s_or_b32 s99, s98, 4
	v_or_b32_e32 v130, s34, v150
	v_bitop3_b32 v18, s98, v220, v150 bitop3:0x36
	v_lshlrev_b64 v[16:17], 11, v[130:131]
	v_lshlrev_b32_e32 v18, 4, v18
	v_lshl_add_u64 v[16:17], s[30:31], 0, v[16:17]
	v_and_b32_e32 v130, 0xf0, v18
	v_lshl_add_u64 v[56:57], v[16:17], 0, v[130:131]
	v_lshl_or_b32 v16, s33, 4, v151
	v_lshrrev_b32_e32 v17, 1, v151
	v_xor_b32_e32 v20, v17, v220
	v_add_u32_e32 v18, s24, v16
	v_mov_b64_e32 v[16:17], s[6:7]
	v_mad_u64_u32 v[18:19], s[34:35], v18, s19, v[16:17]
	v_lshlrev_b32_e32 v20, 4, v20
	s_or_b32 s8, s8, 1
	v_and_b32_e32 v130, 0x70, v20
	s_lshl_b32 s34, s8, 2
	v_lshl_add_u64 v[58:59], v[18:19], 0, v[130:131]
	v_or_b32_e32 v130, s34, v150
	v_bitop3_b32 v20, s99, v220, v150 bitop3:0x36
	v_lshlrev_b64 v[18:19], 11, v[130:131]
	v_lshlrev_b32_e32 v20, 4, v20
	v_lshl_add_u64 v[18:19], s[30:31], 0, v[18:19]
	v_and_b32_e32 v130, 0xf0, v20
	v_lshl_add_u64 v[60:61], v[18:19], 0, v[130:131]
	v_lshl_or_b32 v18, s8, 3, v151
	v_lshrrev_b32_e32 v19, 1, v18
	v_add_u32_e32 v18, s24, v18
	s_lshl_b32 s8, s33, 11
	v_mad_u64_u32 v[16:17], s[30:31], v18, s19, v[16:17]
	s_add_i32 s8, s8, 0
	v_xor_b32_e32 v19, v19, v220
	s_add_i32 s31, s8, 0x4000
	s_mov_b32 m0, s8
	v_lshlrev_b32_e32 v18, 4, v19
	global_load_lds_dwordx4 v[56:57], off
	s_mov_b32 m0, s31
	v_and_b32_e32 v130, 0x70, v18
	global_load_lds_dwordx4 v[58:59], off
	s_add_i32 m0, s8, 0x400
	v_lshl_add_u64 v[62:63], v[16:17], 0, v[130:131]
	global_load_lds_dwordx4 v[60:61], off
	s_add_i32 m0, s8, 0x4400
	v_lshl_add_u64 v[16:17], v[56:57], 0, s[10:11]
	global_load_lds_dwordx4 v[62:63], off
	s_add_i32 m0, s8, 0x8000
	s_add_i32 s31, s8, 0xc000
	v_lshl_add_u64 v[20:21], v[58:59], 0, s[12:13]
	global_load_lds_dwordx4 v[16:17], off
	s_mov_b32 m0, s31
	v_lshl_add_u64 v[18:19], v[60:61], 0, s[10:11]
	global_load_lds_dwordx4 v[20:21], off
	s_add_i32 m0, s8, 0x8400
	v_lshl_add_u64 v[22:23], v[62:63], 0, s[12:13]
	global_load_lds_dwordx4 v[18:19], off
	s_add_i32 m0, s8, 0xc400
	s_lshl_b32 s30, s28, 3
	global_load_lds_dwordx4 v[22:23], off
	v_lshl_add_u64 v[140:141], v[56:57], 0, s[14:15]
	v_lshl_add_u64 v[142:143], v[60:61], 0, s[14:15]
	v_lshl_add_u64 v[144:145], v[58:59], 0, s[16:17]
	v_lshl_add_u64 v[146:147], v[62:63], 0, s[16:17]
	s_add_i32 m0, s8, 0x10000
	s_nop 0
	global_load_lds_dwordx4 v[140:141], off
	s_add_i32 m0, s8, 0x14000
	s_nop 0
	global_load_lds_dwordx4 v[144:145], off
	s_add_i32 m0, s8, 0x10400
	s_nop 0
	global_load_lds_dwordx4 v[142:143], off
	s_add_i32 m0, s8, 0x14400
	s_nop 0
	global_load_lds_dwordx4 v[146:147], off
	s_waitcnt vmcnt(8)
	s_barrier
	v_lshl_add_u64 v[140:141], v[140:141], 0, s[10:11]
	v_lshl_add_u64 v[142:143], v[142:143], 0, s[10:11]
	v_lshl_add_u64 v[144:145], v[144:145], 0, s[12:13]
	v_lshl_add_u64 v[146:147], v[146:147], 0, s[12:13]
	s_mov_b32 s98, s3
	s_mov_b32 s99, s18
	s_mov_b64 s[100:101], s[6:7]
	v_subrev_u32_e32 v140, s3, v140
	v_subrev_u32_e32 v142, s3, v142
	v_subrev_u32_e32 v144, s6, v144
	v_subrev_u32_e32 v146, s6, v146
	s_mov_b32 s33, 1
	v_bitop3_b32 v24, s30, v153, v150 bitop3:0x36
	v_lshlrev_b32_e32 v25, 8, v153
	v_and_b32_e32 v26, 0x700, v25
	v_and_b32_e32 v25, 0x800, v25
	v_lshl_or_b32 v26, v25, 1, v26
	v_lshl_add_u32 v198, v24, 4, v26
	v_xor_b32_e32 v200, 64, v198
	v_lshrrev_b32_e32 v24, 1, v153
	v_xor_b32_e32 v24, v24, v150
	v_lshlrev_b32_e32 v25, 7, v153
	v_lshl_add_u32 v201, v24, 4, v25
	v_xor_b32_e32 v202, 64, v201
	v_add_u32_e32 v247, 0x10000, v198
	v_add_u32_e32 v248, 0x10000, v200
	v_add_u32_e32 v249, 0x10000, v201
	v_add_u32_e32 v250, 0x10000, v202
	ds_read_b128 v[16:19], v198
	ds_read_b128 v[20:23], v200
	ds_read_b128 v[24:27], v198 offset:2048
	ds_read_b128 v[28:31], v200 offset:2048
	ds_read_b128 v[32:35], v198 offset:8192
	ds_read_b128 v[36:39], v200 offset:8192
	ds_read_b128 v[40:43], v198 offset:10240
	ds_read_b128 v[44:47], v200 offset:10240
	s_waitcnt lgkmcnt(7)
	v_mfma_f32_16x16x32_bf16 v[80:83], v[16:19], v[112:115], v[0:3]
	v_mfma_f32_16x16x32_bf16 v[84:87], v[16:19], v[120:123], v[0:3]
	s_waitcnt lgkmcnt(6)
	v_mfma_f32_16x16x32_bf16 v[80:83], v[20:23], v[116:119], v[80:83]
	v_mfma_f32_16x16x32_bf16 v[84:87], v[20:23], v[124:127], v[84:87]
	s_waitcnt lgkmcnt(5)
	v_mfma_f32_16x16x32_bf16 v[88:91], v[24:27], v[112:115], v[0:3]
	v_mfma_f32_16x16x32_bf16 v[92:95], v[24:27], v[120:123], v[0:3]
	s_waitcnt lgkmcnt(4)
	v_mfma_f32_16x16x32_bf16 v[88:91], v[28:31], v[116:119], v[88:91]
	v_mfma_f32_16x16x32_bf16 v[92:95], v[28:31], v[124:127], v[92:95]
	s_waitcnt lgkmcnt(3)
; __device__ __forceinline__ void attn_unit(unsigned char* ws, const float* sub_g, LAS unsigned char* lds, int h, int qb, float negM, float lam) {
;     ...
;     const int qrow0 = qb * 128 + 32 * wq;
;     const bf16_t* Qp = (const bf16_t*)(ws + WS_Q); const bf16_t* Kp = (const bf16_t*)(ws + WS_K); const bf16_t* VTp = (const bf16_t*)(ws + WS_VT);
;     bf16x8 qf[4];
;     {
;         const bf16_t* qp = Qp + (size_t)(qrow0 + r32) * 1024 + (h * 2 + map) * 64 + 8 * hi;
; #pragma unroll
;         for (int d0 = 0; d0 < 4; ++d0) qf[d0] = *(const bf16x8*)(qp + 16 * d0);
;     }
;     const bf16_t* kg[2]; const bf16_t* vg[2];
; #pragma unroll
;     for (int i = 0; i < 2; ++i) {
;         const int g = 2 * wid + i;
;         const int kr = 4 * g + (lane >> 4), kc = (lane & 15) ^ (kr & 15);
;         kg[i] = Kp + (size_t)kr * 1024 + h * 128 + kc * 8;
;         const int vr = 8 * g + (lane >> 3), vc = (lane & 7) ^ ((vr >> 1) & 7);
;         vg[i] = VTp + (size_t)(h * 128 + vr) * NTOK + vc * 8;
;     }
;     const unsigned dmaoff = (unsigned)wid * 2048u;
;     ...
;     f32x16 pa, pb;
;     {
;         f32x16 s0 = negm, s1 = negm;
; #pragma unroll
;         for (int d0 = 0; d0 < 4; ++d0) { s0 = __builtin_amdgcn_mfma_f32_32x32x16_bf16(KFR(0, d0, 0), qf[d0], s0, 0, 0, 0); s1 = __builtin_amdgcn_mfma_f32_32x32x16_bf16(KFR(0, d0, 1), qf[d0], s1, 0, 0, 0); }
; #pragma unroll
;         for (int r = 0; r < 16; ++r) { pa[r] = __builtin_amdgcn_exp2f(s0[r]); pb[r] = __builtin_amdgcn_exp2f(s1[r]); }
;     }
;     asm volatile("s_waitcnt vmcnt(0) lgkmcnt(0)" ::: "memory");
;     __builtin_amdgcn_s_barrier();
;     int bV = 0, bK = AT_BUF, bW = 2 * AT_BUF;
	v_mfma_f32_16x16x32_bf16 v[96:99], v[32:35], v[112:115], v[0:3]
	v_mfma_f32_16x16x32_bf16 v[100:103], v[32:35], v[120:123], v[0:3]
	s_waitcnt lgkmcnt(2)
	v_mfma_f32_16x16x32_bf16 v[96:99], v[36:39], v[116:119], v[96:99]
	v_mfma_f32_16x16x32_bf16 v[100:103], v[36:39], v[124:127], v[100:103]
	s_waitcnt lgkmcnt(1)
	v_mfma_f32_16x16x32_bf16 v[104:107], v[40:43], v[112:115], v[0:3]
	v_mfma_f32_16x16x32_bf16 v[108:111], v[40:43], v[120:123], v[0:3]
	s_waitcnt lgkmcnt(0)
	v_mfma_f32_16x16x32_bf16 v[104:107], v[44:47], v[116:119], v[104:107]
	v_mfma_f32_16x16x32_bf16 v[108:111], v[44:47], v[124:127], v[108:111]
	s_nop 7
	s_nop 1
	v_exp_f32_e32 v183, v80
	v_exp_f32_e32 v184, v81
	v_exp_f32_e32 v185, v82
	v_exp_f32_e32 v186, v83
	v_exp_f32_e32 v187, v84
	v_exp_f32_e32 v188, v85
	v_exp_f32_e32 v189, v86
	v_exp_f32_e32 v190, v87
	v_exp_f32_e32 v191, v88
	v_exp_f32_e32 v192, v89
	v_exp_f32_e32 v193, v90
	v_exp_f32_e32 v194, v91
	v_exp_f32_e32 v195, v92
	v_exp_f32_e32 v196, v93
	v_exp_f32_e32 v197, v94
	v_exp_f32_e32 v199, v95
	v_exp_f32_e32 v203, v96
	v_exp_f32_e32 v204, v97
	v_exp_f32_e32 v205, v98
	v_exp_f32_e32 v206, v99
	v_exp_f32_e32 v207, v100
	v_exp_f32_e32 v208, v101
	v_exp_f32_e32 v209, v102
	v_exp_f32_e32 v210, v103
	v_exp_f32_e32 v211, v104
	v_exp_f32_e32 v213, v105
	v_exp_f32_e32 v214, v106
	v_exp_f32_e32 v215, v107
	v_exp_f32_e32 v216, v108
	v_exp_f32_e32 v217, v109
	v_exp_f32_e32 v218, v110
	v_exp_f32_e32 v219, v111
	v_mov_b32_e32 v16, 0
	v_mov_b32_e32 v17, 0
	v_mov_b32_e32 v18, 0
	v_mov_b32_e32 v19, 0
	v_mov_b32_e32 v20, 0
	v_mov_b32_e32 v21, 0
	v_mov_b32_e32 v22, 0
	v_mov_b32_e32 v23, 0
	v_mov_b32_e32 v24, 0
	v_mov_b32_e32 v25, 0
	v_mov_b32_e32 v26, 0
	v_mov_b32_e32 v27, 0
	v_mov_b32_e32 v28, 0
	v_mov_b32_e32 v29, 0
	v_mov_b32_e32 v30, 0
	v_mov_b32_e32 v31, 0
	v_mov_b32_e32 v32, 0
	v_mov_b32_e32 v33, 0
	v_mov_b32_e32 v34, 0
	v_mov_b32_e32 v35, 0
	v_mov_b32_e32 v36, 0
	v_mov_b32_e32 v37, 0
	v_mov_b32_e32 v38, 0
	v_mov_b32_e32 v39, 0
	v_mov_b32_e32 v40, 0
	v_mov_b32_e32 v41, 0
	v_mov_b32_e32 v42, 0
	v_mov_b32_e32 v43, 0
	v_mov_b32_e32 v44, 0
	v_mov_b32_e32 v45, 0
	v_mov_b32_e32 v46, 0
	v_mov_b32_e32 v47, 0
	v_mov_b32_e32 v48, 0
	v_mov_b32_e32 v49, 0
	v_mov_b32_e32 v50, 0
	v_mov_b32_e32 v51, 0
	v_mov_b32_e32 v52, 0
	v_mov_b32_e32 v53, 0
	v_mov_b32_e32 v54, 0
	v_mov_b32_e32 v55, 0
	v_mov_b32_e32 v56, 0
	v_mov_b32_e32 v57, 0
	v_mov_b32_e32 v58, 0
	v_mov_b32_e32 v59, 0
	v_mov_b32_e32 v60, 0
	v_mov_b32_e32 v61, 0
	v_mov_b32_e32 v62, 0
	v_mov_b32_e32 v63, 0
	v_mov_b32_e32 v64, 0
	v_mov_b32_e32 v65, 0
	v_mov_b32_e32 v66, 0
	v_mov_b32_e32 v67, 0
	v_mov_b32_e32 v68, 0
	v_mov_b32_e32 v69, 0
	v_mov_b32_e32 v70, 0
	v_mov_b32_e32 v71, 0
	v_mov_b32_e32 v72, 0
	v_mov_b32_e32 v73, 0
	v_mov_b32_e32 v74, 0
	v_mov_b32_e32 v75, 0
	v_mov_b32_e32 v76, 0
	v_mov_b32_e32 v77, 0
	v_mov_b32_e32 v78, 0
	v_mov_b32_e32 v79, 0
	v_mov_b32_e32 v222, 0
	v_mov_b32_e32 v223, 0
	s_waitcnt vmcnt(4)
	s_barrier
	ds_read_b128 v[4:7], v198 offset:32768
	ds_read_b128 v[8:11], v200 offset:32768
	ds_read_b128 v[12:15], v198 offset:34816
	s_branch .Lattn_c1
.Lpro_b:
	v_readfirstlane_b32 s25, v220
	s_bfe_u32 s29, s25, 0x20006
	s_lshl_b32 s8, s20, 4
	s_and_b32 s8, s8, 0xffffff80
	s_lshl_b32 s21, s29, 5
	s_or_b32 s21, s21, s8
	s_lshr_b32 s28, s25, 8
	v_or_b32_e32 v16, s21, v153
	s_lshl_b32 s8, s20, 7
	v_ashrrev_i32_e32 v17, 31, v16
	s_and_b32 s24, s8, 0x380
	s_lshl_b32 s8, s28, 6
	v_lshlrev_b64 v[16:17], 11, v[16:17]
	s_add_i32 s8, s8, s24
	v_lshl_add_u64 v[16:17], s[4:5], 0, v[16:17]
	s_lshl_b32 s8, s8, 1
	v_lshl_add_u64 v[16:17], v[16:17], 0, s[8:9]
	v_lshlrev_b32_e32 v130, 4, v150
	s_mov_b64 s[34:35], 0x8000
	v_lshl_add_u64 v[16:17], v[16:17], 0, v[130:131]
	v_lshl_add_u64 v[18:19], v[16:17], 0, s[34:35]
	s_lshr_b32 s33, s25, 6
	s_lshr_b32 s8, s25, 5
	s_lshl_b32 s30, s24, 1
	s_add_u32 s30, s3, s30
	s_addc_u32 s31, s18, 0
	s_lshl_b32 s34, s33, 3
	s_bfe_u32 s98, s25, 0x10007
	s_lshl_b32 s98, s98, 3
	s_or_b32 s99, s98, 4
	v_or_b32_e32 v130, s34, v150
	v_bitop3_b32 v18, s98, v220, v150 bitop3:0x36
	v_lshlrev_b64 v[16:17], 11, v[130:131]
	v_lshlrev_b32_e32 v18, 4, v18
	v_lshl_add_u64 v[16:17], s[30:31], 0, v[16:17]
	v_and_b32_e32 v130, 0xf0, v18
	v_lshl_add_u64 v[56:57], v[16:17], 0, v[130:131]
	v_lshl_or_b32 v16, s33, 4, v151
	v_lshrrev_b32_e32 v17, 1, v151
	v_xor_b32_e32 v20, v17, v220
	v_add_u32_e32 v18, s24, v16
	v_mov_b64_e32 v[16:17], s[6:7]
	v_mad_u64_u32 v[18:19], s[34:35], v18, s19, v[16:17]
	v_lshlrev_b32_e32 v20, 4, v20
	s_or_b32 s8, s8, 1
	v_and_b32_e32 v130, 0x70, v20
	s_lshl_b32 s34, s8, 2
	v_lshl_add_u64 v[58:59], v[18:19], 0, v[130:131]
	v_or_b32_e32 v130, s34, v150
	v_bitop3_b32 v20, s99, v220, v150 bitop3:0x36
	v_lshlrev_b64 v[18:19], 11, v[130:131]
	v_lshlrev_b32_e32 v20, 4, v20
	v_lshl_add_u64 v[18:19], s[30:31], 0, v[18:19]
	v_and_b32_e32 v130, 0xf0, v20
	v_lshl_add_u64 v[60:61], v[18:19], 0, v[130:131]
	v_lshl_or_b32 v18, s8, 3, v151
	v_lshrrev_b32_e32 v19, 1, v18
	v_add_u32_e32 v18, s24, v18
	s_lshl_b32 s8, s33, 11
	v_mad_u64_u32 v[16:17], s[30:31], v18, s19, v[16:17]
	s_add_i32 s8, s8, 0
	v_xor_b32_e32 v19, v19, v220
	s_add_i32 s31, s8, 0x4000
	s_mov_b32 m0, s8
	v_lshlrev_b32_e32 v18, 4, v19
	s_mov_b32 m0, s31
	v_and_b32_e32 v130, 0x70, v18
	s_add_i32 m0, s8, 0x400
	v_lshl_add_u64 v[62:63], v[16:17], 0, v[130:131]
	s_add_i32 m0, s8, 0x4400
	v_lshl_add_u64 v[16:17], v[56:57], 0, s[10:11]
	s_add_i32 m0, s8, 0x8000
	s_add_i32 s31, s8, 0xc000
	v_lshl_add_u64 v[20:21], v[58:59], 0, s[12:13]
	s_mov_b32 m0, s31
	v_lshl_add_u64 v[18:19], v[60:61], 0, s[10:11]
	s_add_i32 m0, s8, 0x8400
; #define AT_DMA(B) do { _Pragma("unroll") for (int i_ = 0; i_ < 2; ++i_) { \
;         __builtin_amdgcn_global_load_lds((const unsigned*)kg[i_], (LAS unsigned*)(lds + (B) + dmaoff + i_ * 1024), 16, 0, 0); \
;         __builtin_amdgcn_global_load_lds((const unsigned*)vg[i_], (LAS unsigned*)(lds + (B) + AT_KBYTES + dmaoff + i_ * 1024), 16, 0, 0); } } while (0)
; #define AT_ADV() do { kg[0] += 64 * 1024; kg[1] += 64 * 1024; vg[0] += 64; vg[1] += 64; } while (0)
; __device__ __forceinline__ void attn_unit(unsigned char* ws, const float* sub_g, LAS unsigned char* lds, int h, int qb, float negM, float lam) {
;     ...
;     const unsigned dmaoff = (unsigned)wid * 2048u;
;     ...
;     int kad[4], vad[4];
; #pragma unroll
;     for (int d0 = 0; d0 < 4; ++d0) kad[d0] = r32 * 256 + (((map * 8 + 2 * d0 + hi) ^ (r32 & 15)) << 4);
; #pragma unroll
;     for (int j = 0; j < 4; ++j) vad[j] = AT_KBYTES + r32 * 128 + (((2 * j + hi) ^ ((r32 >> 1) & 7)) << 4);
;     ...
;     f32x16 o[4];
; #pragma unroll
;     for (int b = 0; b < 4; ++b)
; #pragma unroll
;         for (int r = 0; r < 16; ++r) o[b][r] = 0.f;
;     f32x16 negm;
; #pragma unroll
;     for (int r = 0; r < 16; ++r) negm[r] = negM;
;     float l0 = 0.f, l1 = 0.f;
;     AT_DMA(0); AT_ADV();
;     asm volatile("s_waitcnt vmcnt(0)" ::: "memory");
;     __builtin_amdgcn_s_barrier();
;     AT_DMA(AT_BUF); AT_ADV();
;     f32x16 pa, pb;
;     {
;         f32x16 s0 = negm, s1 = negm;
; #pragma unroll
;         for (int d0 = 0; d0 < 4; ++d0) { s0 = __builtin_amdgcn_mfma_f32_32x32x16_bf16(KFR(0, d0, 0), qf[d0], s0, 0, 0, 0); s1 = __builtin_amdgcn_mfma_f32_32x32x16_bf16(KFR(0, d0, 1), qf[d0], s1, 0, 0, 0); }
; #pragma unroll
;         for (int r = 0; r < 16; ++r) { pa[r] = __builtin_amdgcn_exp2f(s0[r]); pb[r] = __builtin_amdgcn_exp2f(s1[r]); }
;     }
;     asm volatile("s_waitcnt vmcnt(0) lgkmcnt(0)" ::: "memory");
;     __builtin_amdgcn_s_barrier();
;     int bV = 0, bK = AT_BUF, bW = 2 * AT_BUF;
	v_lshl_add_u64 v[22:23], v[62:63], 0, s[12:13]
	s_add_i32 m0, s8, 0xc400
	s_lshl_b32 s30, s28, 3
	v_lshl_add_u64 v[140:141], v[56:57], 0, s[14:15]
	v_lshl_add_u64 v[142:143], v[60:61], 0, s[14:15]
	v_lshl_add_u64 v[144:145], v[58:59], 0, s[16:17]
	v_lshl_add_u64 v[146:147], v[62:63], 0, s[16:17]
	s_add_i32 m0, s8, 0x10000
	s_nop 0
	global_load_lds_dwordx4 v[140:141], off
	s_add_i32 m0, s8, 0x14000
	s_nop 0
	global_load_lds_dwordx4 v[144:145], off
	s_add_i32 m0, s8, 0x10400
	s_nop 0
	global_load_lds_dwordx4 v[142:143], off
	s_add_i32 m0, s8, 0x14400
	s_nop 0
	global_load_lds_dwordx4 v[146:147], off
	v_lshl_add_u64 v[140:141], v[140:141], 0, s[10:11]
	v_lshl_add_u64 v[142:143], v[142:143], 0, s[10:11]
	v_lshl_add_u64 v[144:145], v[144:145], 0, s[12:13]
	v_lshl_add_u64 v[146:147], v[146:147], 0, s[12:13]
	s_mov_b32 s98, s3
	s_mov_b32 s99, s18
	s_mov_b64 s[100:101], s[6:7]
	v_subrev_u32_e32 v140, s3, v140
	v_subrev_u32_e32 v142, s3, v142
	v_subrev_u32_e32 v144, s6, v144
	v_subrev_u32_e32 v146, s6, v146
	s_mov_b32 s33, 1
	v_bitop3_b32 v24, s30, v153, v150 bitop3:0x36
	v_lshlrev_b32_e32 v25, 8, v153
	v_and_b32_e32 v26, 0x700, v25
	v_and_b32_e32 v25, 0x800, v25
	v_lshl_or_b32 v26, v25, 1, v26
	v_lshl_add_u32 v198, v24, 4, v26
	v_xor_b32_e32 v200, 64, v198
	v_lshrrev_b32_e32 v24, 1, v153
	v_xor_b32_e32 v24, v24, v150
	v_lshlrev_b32_e32 v25, 7, v153
	v_lshl_add_u32 v201, v24, 4, v25
	v_xor_b32_e32 v202, 64, v201
	v_add_u32_e32 v247, 0x10000, v198
	v_add_u32_e32 v248, 0x10000, v200
	v_add_u32_e32 v249, 0x10000, v201
	v_add_u32_e32 v250, 0x10000, v202
	ds_read_b128 v[16:19], v198
	ds_read_b128 v[20:23], v200
	ds_read_b128 v[24:27], v198 offset:2048
	ds_read_b128 v[28:31], v200 offset:2048
	ds_read_b128 v[32:35], v198 offset:8192
	ds_read_b128 v[36:39], v200 offset:8192
	ds_read_b128 v[40:43], v198 offset:10240
	ds_read_b128 v[44:47], v200 offset:10240
	s_waitcnt lgkmcnt(7)
	v_mfma_f32_16x16x32_bf16 v[80:83], v[16:19], v[112:115], v[0:3]
	v_mfma_f32_16x16x32_bf16 v[84:87], v[16:19], v[120:123], v[0:3]
	s_waitcnt lgkmcnt(6)
	v_mfma_f32_16x16x32_bf16 v[80:83], v[20:23], v[116:119], v[80:83]
	v_mfma_f32_16x16x32_bf16 v[84:87], v[20:23], v[124:127], v[84:87]
	s_waitcnt lgkmcnt(5)
	v_mfma_f32_16x16x32_bf16 v[88:91], v[24:27], v[112:115], v[0:3]
	v_mfma_f32_16x16x32_bf16 v[92:95], v[24:27], v[120:123], v[0:3]
	s_waitcnt lgkmcnt(4)
	v_mfma_f32_16x16x32_bf16 v[88:91], v[28:31], v[116:119], v[88:91]
	v_mfma_f32_16x16x32_bf16 v[92:95], v[28:31], v[124:127], v[92:95]
	s_waitcnt lgkmcnt(3)
	v_mfma_f32_16x16x32_bf16 v[96:99], v[32:35], v[112:115], v[0:3]
	v_mfma_f32_16x16x32_bf16 v[100:103], v[32:35], v[120:123], v[0:3]
	s_waitcnt lgkmcnt(2)
	v_mfma_f32_16x16x32_bf16 v[96:99], v[36:39], v[116:119], v[96:99]
	v_mfma_f32_16x16x32_bf16 v[100:103], v[36:39], v[124:127], v[100:103]
	s_waitcnt lgkmcnt(1)
	v_mfma_f32_16x16x32_bf16 v[104:107], v[40:43], v[112:115], v[0:3]
	v_mfma_f32_16x16x32_bf16 v[108:111], v[40:43], v[120:123], v[0:3]
	s_waitcnt lgkmcnt(0)
	v_mfma_f32_16x16x32_bf16 v[104:107], v[44:47], v[116:119], v[104:107]
	v_mfma_f32_16x16x32_bf16 v[108:111], v[44:47], v[124:127], v[108:111]
	s_nop 7
	s_nop 1
	v_exp_f32_e32 v183, v80
	v_exp_f32_e32 v184, v81
	v_exp_f32_e32 v185, v82
	v_exp_f32_e32 v186, v83
	v_exp_f32_e32 v187, v84
	v_exp_f32_e32 v188, v85
	v_exp_f32_e32 v189, v86
	v_exp_f32_e32 v190, v87
	v_exp_f32_e32 v191, v88
	v_exp_f32_e32 v192, v89
	v_exp_f32_e32 v193, v90
	v_exp_f32_e32 v194, v91
	v_exp_f32_e32 v195, v92
	v_exp_f32_e32 v196, v93
	v_exp_f32_e32 v197, v94
	v_exp_f32_e32 v199, v95
	v_exp_f32_e32 v203, v96
	v_exp_f32_e32 v204, v97
	v_exp_f32_e32 v205, v98
	v_exp_f32_e32 v206, v99
	v_exp_f32_e32 v207, v100
	v_exp_f32_e32 v208, v101
	v_exp_f32_e32 v209, v102
	v_exp_f32_e32 v210, v103
	v_exp_f32_e32 v211, v104
	v_exp_f32_e32 v213, v105
	v_exp_f32_e32 v214, v106
	v_exp_f32_e32 v215, v107
	v_exp_f32_e32 v216, v108
	v_exp_f32_e32 v217, v109
	v_exp_f32_e32 v218, v110
	v_exp_f32_e32 v219, v111
	v_mov_b32_e32 v16, 0
	v_mov_b32_e32 v17, 0
	v_mov_b32_e32 v18, 0
	v_mov_b32_e32 v19, 0
	v_mov_b32_e32 v20, 0
	v_mov_b32_e32 v21, 0
	v_mov_b32_e32 v22, 0
	v_mov_b32_e32 v23, 0
	v_mov_b32_e32 v24, 0
	v_mov_b32_e32 v25, 0
	v_mov_b32_e32 v26, 0
	v_mov_b32_e32 v27, 0
	v_mov_b32_e32 v28, 0
	v_mov_b32_e32 v29, 0
	v_mov_b32_e32 v30, 0
	v_mov_b32_e32 v31, 0
	v_mov_b32_e32 v32, 0
	v_mov_b32_e32 v33, 0
	v_mov_b32_e32 v34, 0
	v_mov_b32_e32 v35, 0
	v_mov_b32_e32 v36, 0
	v_mov_b32_e32 v37, 0
	v_mov_b32_e32 v38, 0
	v_mov_b32_e32 v39, 0
	v_mov_b32_e32 v40, 0
	v_mov_b32_e32 v41, 0
	v_mov_b32_e32 v42, 0
	v_mov_b32_e32 v43, 0
	v_mov_b32_e32 v44, 0
	v_mov_b32_e32 v45, 0
	v_mov_b32_e32 v46, 0
	v_mov_b32_e32 v47, 0
	v_mov_b32_e32 v48, 0
	v_mov_b32_e32 v49, 0
	v_mov_b32_e32 v50, 0
	v_mov_b32_e32 v51, 0
	v_mov_b32_e32 v52, 0
	v_mov_b32_e32 v53, 0
	v_mov_b32_e32 v54, 0
	v_mov_b32_e32 v55, 0
	v_mov_b32_e32 v56, 0
	v_mov_b32_e32 v57, 0
	v_mov_b32_e32 v58, 0
	v_mov_b32_e32 v59, 0
	v_mov_b32_e32 v60, 0
	v_mov_b32_e32 v61, 0
	v_mov_b32_e32 v62, 0
	v_mov_b32_e32 v63, 0
	v_mov_b32_e32 v64, 0
	v_mov_b32_e32 v65, 0
	v_mov_b32_e32 v66, 0
	v_mov_b32_e32 v67, 0
	v_mov_b32_e32 v68, 0
	v_mov_b32_e32 v69, 0
	v_mov_b32_e32 v70, 0
	v_mov_b32_e32 v71, 0
	v_mov_b32_e32 v72, 0
	v_mov_b32_e32 v73, 0
	v_mov_b32_e32 v74, 0
	v_mov_b32_e32 v75, 0
	v_mov_b32_e32 v76, 0
	v_mov_b32_e32 v77, 0
	v_mov_b32_e32 v78, 0
	v_mov_b32_e32 v79, 0
	v_mov_b32_e32 v222, 0
	v_mov_b32_e32 v223, 0
	s_waitcnt vmcnt(4)
	s_barrier
	ds_read_b128 v[4:7], v198 offset:32768
	ds_read_b128 v[8:11], v200 offset:32768
	ds_read_b128 v[12:15], v198 offset:34816
	s_branch .Lattn_c1

; __device__ __forceinline__ void attn_unit(unsigned char* ws, const float* sub_g, LAS unsigned char* lds, int h, int qb, float negM, float lam) {
;     ...
;         const bf16_t* qp = Qp + (size_t)(qrow0 + r32) * 1024 + (h * 2 + map) * 64 + 8 * hi;
; #pragma unroll
;         for (int d0 = 0; d0 < 4; ++d0) qf[d0] = *(const bf16x8*)(qp + 16 * d0);
;     }
;     const bf16_t* kg[2]; const bf16_t* vg[2];
; #pragma unroll
;     for (int i = 0; i < 2; ++i) {
;         const int g = 2 * wid + i;
;         const int kr = 4 * g + (lane >> 4), kc = (lane & 15) ^ (kr & 15);
;         kg[i] = Kp + (size_t)kr * 1024 + h * 128 + kc * 8;
;         const int vr = 8 * g + (lane >> 3), vc = (lane & 7) ^ ((vr >> 1) & 7);
;         vg[i] = VTp + (size_t)(h * 128 + vr) * NTOK + vc * 8;
;     }
;     const unsigned dmaoff = (unsigned)wid * 2048u;
;     ...
;     int kad[4], vad[4];
; #pragma unroll
;     for (int d0 = 0; d0 < 4; ++d0) kad[d0] = r32 * 256 + (((map * 8 + 2 * d0 + hi) ^ (r32 & 15)) << 4);
; #pragma unroll
;     for (int j = 0; j < 4; ++j) vad[j] = AT_KBYTES + r32 * 128 + (((2 * j + hi) ^ ((r32 >> 1) & 7)) << 4);
;     ...
;     f32x16 o[4];
; #pragma unroll
;     for (int b = 0; b < 4; ++b)
; #pragma unroll
;         for (int r = 0; r < 16; ++r) o[b][r] = 0.f;
;     f32x16 negm;
; #pragma unroll
;     for (int r = 0; r < 16; ++r) negm[r] = negM;
;     float l0 = 0.f, l1 = 0.f;
;     AT_DMA(0); AT_ADV();
;     ...
;     {
;         float a0 = 0.f, a1 = 0.f;
; #pragma unroll
;         for (int r = 0; r < 16; ++r) { a0 += pa[r]; a1 += pb[r]; }
;         l0 += a0; l1 += a1;
;         pw[0] = (u32x4){cvtpk(pa[0], pa[1]), cvtpk(pa[2], pa[3]), cvtpk(pa[4], pa[5]), cvtpk(pa[6], pa[7])};
;         pw[1] = (u32x4){cvtpk(pa[8], pa[9]), cvtpk(pa[10], pa[11]), cvtpk(pa[12], pa[13]), cvtpk(pa[14], pa[15])};
;         pw[2] = (u32x4){cvtpk(pb[0], pb[1]), cvtpk(pb[2], pb[3]), cvtpk(pb[4], pb[5]), cvtpk(pb[6], pb[7])};
;         pw[3] = (u32x4){cvtpk(pb[8], pb[9]), cvtpk(pb[10], pb[11]), cvtpk(pb[12], pb[13]), cvtpk(pb[14], pb[15])};
; #pragma unroll
;         for (int j = 0; j < 4; ++j)
; #pragma unroll
;             for (int b = 0; b < 4; ++b) o[b] = __builtin_amdgcn_mfma_f32_32x32x16_bf16(VFR(bV, j, b), __builtin_bit_cast(bf16x8, pw[j]), o[b], 0, 0, 0);
;     }
;     float l = l0 + l1;
;     ...
;     asm volatile("s_waitcnt vmcnt(0) lgkmcnt(0)" ::: "memory");
;     __builtin_amdgcn_s_barrier();
.Lattn_exit:
	s_waitcnt lgkmcnt(0)
	ds_read_b128 v[80:83], v249 offset:49152
	ds_read_b128 v[84:87], v249 offset:51200
	ds_read_b128 v[88:91], v249 offset:53248
	ds_read_b128 v[92:95], v249 offset:55296
	ds_read_b128 v[96:99], v249 offset:57344
	ds_read_b128 v[100:103], v249 offset:59392
	ds_read_b128 v[104:107], v249 offset:61440
	ds_read_b128 v[108:111], v249 offset:63488
	v_add_f32_e32 v222, v222, v183
	v_add_f32_e32 v223, v223, v187
	v_add_f32_e32 v222, v222, v184
	v_add_f32_e32 v223, v223, v188
	v_add_f32_e32 v222, v222, v185
	v_add_f32_e32 v223, v223, v189
	v_add_f32_e32 v222, v222, v186
	v_add_f32_e32 v223, v223, v190
	v_add_f32_e32 v222, v222, v191
	v_add_f32_e32 v223, v223, v195
	v_add_f32_e32 v222, v222, v192
	v_add_f32_e32 v223, v223, v196
	v_add_f32_e32 v222, v222, v193
	v_add_f32_e32 v223, v223, v197
	v_add_f32_e32 v222, v222, v194
	v_add_f32_e32 v223, v223, v199
	v_add_f32_e32 v222, v222, v203
	v_add_f32_e32 v223, v223, v207
	v_add_f32_e32 v222, v222, v204
	v_add_f32_e32 v223, v223, v208
	v_add_f32_e32 v222, v222, v205
	v_add_f32_e32 v223, v223, v209
	v_add_f32_e32 v222, v222, v206
	v_add_f32_e32 v223, v223, v210
	v_add_f32_e32 v222, v222, v211
	v_add_f32_e32 v223, v223, v216
	v_add_f32_e32 v222, v222, v213
	v_add_f32_e32 v223, v223, v217
	v_add_f32_e32 v222, v222, v214
	v_add_f32_e32 v223, v223, v218
	v_add_f32_e32 v222, v222, v215
	v_add_f32_e32 v223, v223, v219
	v_cvt_pk_bf16_f32 v232, v183, v184
	v_cvt_pk_bf16_f32 v233, v185, v186
	v_cvt_pk_bf16_f32 v234, v191, v192
	v_cvt_pk_bf16_f32 v235, v193, v194
	v_cvt_pk_bf16_f32 v236, v187, v188
	v_cvt_pk_bf16_f32 v237, v189, v190
	v_cvt_pk_bf16_f32 v238, v195, v196
	v_cvt_pk_bf16_f32 v239, v197, v199
	v_cvt_pk_bf16_f32 v228, v203, v204
	v_cvt_pk_bf16_f32 v229, v205, v206
	v_cvt_pk_bf16_f32 v230, v211, v213
	v_cvt_pk_bf16_f32 v231, v214, v215
	v_cvt_pk_bf16_f32 v240, v207, v208
	v_cvt_pk_bf16_f32 v241, v209, v210
	v_cvt_pk_bf16_f32 v242, v216, v217
	v_cvt_pk_bf16_f32 v243, v218, v219
	s_lshl_b32 s8, s29, 14
	s_add_i32 s29, s8, 0x10000
	s_waitcnt lgkmcnt(7)
	v_mfma_f32_16x16x32_bf16 v[64:67], v[80:83], v[232:235], v[64:67]
	v_mfma_f32_16x16x32_bf16 v[68:71], v[80:83], v[236:239], v[68:71]
	s_waitcnt lgkmcnt(6)
	v_mfma_f32_16x16x32_bf16 v[72:75], v[84:87], v[232:235], v[72:75]
	v_mfma_f32_16x16x32_bf16 v[76:79], v[84:87], v[236:239], v[76:79]
	s_waitcnt lgkmcnt(5)
	v_mfma_f32_16x16x32_bf16 v[48:51], v[88:91], v[232:235], v[48:51]
	v_mfma_f32_16x16x32_bf16 v[52:55], v[88:91], v[236:239], v[52:55]
	s_waitcnt lgkmcnt(4)
	v_mfma_f32_16x16x32_bf16 v[56:59], v[92:95], v[232:235], v[56:59]
	v_mfma_f32_16x16x32_bf16 v[60:63], v[92:95], v[236:239], v[60:63]
	s_waitcnt lgkmcnt(3)
	v_mfma_f32_16x16x32_bf16 v[32:35], v[96:99], v[232:235], v[32:35]
	v_mfma_f32_16x16x32_bf16 v[36:39], v[96:99], v[236:239], v[36:39]
	s_waitcnt lgkmcnt(2)
	v_mfma_f32_16x16x32_bf16 v[40:43], v[100:103], v[232:235], v[40:43]
	v_mfma_f32_16x16x32_bf16 v[44:47], v[100:103], v[236:239], v[44:47]
	s_waitcnt lgkmcnt(1)
	v_mfma_f32_16x16x32_bf16 v[16:19], v[104:107], v[232:235], v[16:19]
	v_mfma_f32_16x16x32_bf16 v[20:23], v[104:107], v[236:239], v[20:23]
	s_waitcnt lgkmcnt(0)
	v_mfma_f32_16x16x32_bf16 v[24:27], v[108:111], v[232:235], v[24:27]
	v_mfma_f32_16x16x32_bf16 v[28:31], v[108:111], v[236:239], v[28:31]
	ds_read_b128 v[4:7], v250 offset:49152
	ds_read_b128 v[8:11], v250 offset:51200
	ds_read_b128 v[12:15], v250 offset:53248
	ds_read_b128 v[224:227], v250 offset:55296
	ds_read_b128 v[112:115], v250 offset:57344
	ds_read_b128 v[116:119], v250 offset:59392
	ds_read_b128 v[120:123], v250 offset:61440
	ds_read_b128 v[124:127], v250 offset:63488
	s_waitcnt lgkmcnt(7)
	v_mfma_f32_16x16x32_bf16 v[64:67], v[4:7], v[228:231], v[64:67]
	v_mfma_f32_16x16x32_bf16 v[68:71], v[4:7], v[240:243], v[68:71]
	s_waitcnt lgkmcnt(6)
	v_mfma_f32_16x16x32_bf16 v[72:75], v[8:11], v[228:231], v[72:75]
	v_mfma_f32_16x16x32_bf16 v[76:79], v[8:11], v[240:243], v[76:79]
	s_waitcnt lgkmcnt(5)
	v_mfma_f32_16x16x32_bf16 v[48:51], v[12:15], v[228:231], v[48:51]
	v_mfma_f32_16x16x32_bf16 v[52:55], v[12:15], v[240:243], v[52:55]
	s_waitcnt lgkmcnt(4)
	v_mfma_f32_16x16x32_bf16 v[56:59], v[224:227], v[228:231], v[56:59]
	v_mfma_f32_16x16x32_bf16 v[60:63], v[224:227], v[240:243], v[60:63]
	s_waitcnt lgkmcnt(3)
	v_mfma_f32_16x16x32_bf16 v[32:35], v[112:115], v[228:231], v[32:35]
	v_mfma_f32_16x16x32_bf16 v[36:39], v[112:115], v[240:243], v[36:39]
	s_waitcnt lgkmcnt(2)
	v_mfma_f32_16x16x32_bf16 v[40:43], v[116:119], v[228:231], v[40:43]
	v_mfma_f32_16x16x32_bf16 v[44:47], v[116:119], v[240:243], v[44:47]
	s_waitcnt lgkmcnt(1)
	v_mfma_f32_16x16x32_bf16 v[16:19], v[120:123], v[228:231], v[16:19]
	v_mfma_f32_16x16x32_bf16 v[20:23], v[120:123], v[240:243], v[20:23]
	s_waitcnt lgkmcnt(0)
	v_mfma_f32_16x16x32_bf16 v[24:27], v[124:127], v[228:231], v[24:27]
	v_mfma_f32_16x16x32_bf16 v[28:31], v[124:127], v[240:243], v[28:31]
	s_waitcnt vmcnt(0)
	s_barrier
	s_cmpk_gt_i32 s20, 0xff
	s_cbranch_scc1 .Lpf_skip
	s_add_i32 s36, s21, 0x1000
	v_or_b32_e32 v96, s36, v153
	v_ashrrev_i32_e32 v97, 31, v96
	v_lshlrev_b64 v[96:97], 11, v[96:97]
	v_lshl_add_u64 v[96:97], s[4:5], 0, v[96:97]
	s_lshl_b32 s36, s28, 6
	s_add_i32 s36, s36, s24
	s_lshl_b32 s36, s36, 1
	s_mov_b32 s37, 0
	v_lshl_add_u64 v[96:97], v[96:97], 0, s[36:37]
	v_lshlrev_b32_e32 v98, 4, v150
	v_mov_b32_e32 v99, 0
	v_lshl_add_u64 v[96:97], v[96:97], 0, v[98:99]
	s_mov_b64 s[34:35], 0x8000
	v_lshl_add_u64 v[98:99], v[96:97], 0, s[34:35]
	global_load_dwordx4 v[112:115], v[96:97], off
	global_load_dwordx4 v[116:119], v[96:97], off offset:64
	global_load_dwordx4 v[120:123], v[98:99], off
	global_load_dwordx4 v[124:127], v[98:99], off offset:64
	s_lshr_b32 s8, s25, 6
	s_lshl_b32 s8, s8, 11
	s_sub_u32 s98, s3, 0x60000
	s_subb_u32 s99, s18, 0
	s_sub_u32 s100, s6, 0x180
	s_subb_u32 s101, s7, 0
	s_mov_b32 m0, s8
	s_nop 0
	global_load_lds_dwordx4 v140, s[98:99]
	s_add_i32 m0, s8, 0x4000
	s_nop 0
	global_load_lds_dwordx4 v144, s[100:101]
	s_add_i32 m0, s8, 0x400
	s_nop 0
	global_load_lds_dwordx4 v142, s[98:99]
	s_add_i32 m0, s8, 0x4400
	s_nop 0
	global_load_lds_dwordx4 v146, s[100:101]
	s_add_u32 s98, s98, 0x20000
	s_addc_u32 s99, s99, 0
	s_add_u32 s100, s100, 0x80
	s_addc_u32 s101, s101, 0
	s_add_i32 m0, s8, 0x8000
	s_nop 0
	global_load_lds_dwordx4 v140, s[98:99]
	s_add_i32 m0, s8, 0xc000
	s_nop 0
	global_load_lds_dwordx4 v144, s[100:101]
	s_add_i32 m0, s8, 0x8400
	s_nop 0
	global_load_lds_dwordx4 v142, s[98:99]
	s_add_i32 m0, s8, 0xc400
	s_nop 0
	global_load_lds_dwordx4 v146, s[100:101]
; #define LAS __attribute__((address_space(3)))
; __device__ __forceinline__ unsigned cvtpk(float lo, float hi) { f32x2 v = {lo, hi}; bf16x2_t b = __builtin_convertvector(v, bf16x2_t); return __builtin_bit_cast(unsigned, b); }
; __device__ __forceinline__ void attn_unit(unsigned char* ws, const float* sub_g, LAS unsigned char* lds, int h, int qb, float negM, float lam) {
;     ...
;     float l = l0 + l1;
;     ...
;     asm volatile("s_waitcnt vmcnt(0) lgkmcnt(0)" ::: "memory");
;     __builtin_amdgcn_s_barrier();
;     l += __shfl_xor(l, 32);
;     const float inv = 1.0f / l;
;     LAS float* xw = (LAS float*)(lds + AT_XOFF + wq * 16384);
;     if (map == 1) {
;         const float f = inv * lam;
; #pragma unroll
;         for (int b = 0; b < 4; ++b)
; #pragma unroll
;             for (int r = 0; r < 16; ++r) xw[(b * 16 + r) * 64 + lane] = o[b][r] * f;
;     }
;     __syncthreads();
;     if (map == 0) {
;         float ss = 0.f;
; #pragma unroll
;         for (int b = 0; b < 4; ++b)
; #pragma unroll
;             for (int r = 0; r < 16; ++r) { const float v = o[b][r] * inv - xw[(b * 16 + r) * 64 + lane]; o[b][r] = v; ss += v * v; }
;         ss += __shfl_xor(ss, 32);
;         const float rs = __builtin_amdgcn_rsqf(ss * (1.0f / VD) + EPS) * (1.0f - LAM_INIT);
;         LAS unsigned char* stg = (LAS unsigned char*)xw;
; #pragma unroll
;         for (int b = 0; b < 4; ++b)
; #pragma unroll
;             for (int r4 = 0; r4 < 4; ++r4) {
;                 const int dv = 32 * b + 8 * r4 + 4 * hi;
;                 const f32x4 sg = *(const f32x4*)(sub_g + dv);
;                 u32x2 w; w.x = cvtpk(o[b][4 * r4 + 0] * rs * sg[0], o[b][4 * r4 + 1] * rs * sg[1]); w.y = cvtpk(o[b][4 * r4 + 2] * rs * sg[2], o[b][4 * r4 + 3] * rs * sg[3]);
;                 *(LAS u32x2*)(stg + r32 * 272 + dv * 2) = w;
;             }
;         asm volatile("s_waitcnt lgkmcnt(0)" ::: "memory");
;         const bf16_t* GA = (const bf16_t*)(ws + WS_GA); bf16_t* MIX = (bf16_t*)(ws + WS_MIX);
;         u32x4 gvs[8];
; #pragma unroll
;         for (int i = 0; i < 8; ++i) gvs[i] = *(const u32x4*)(GA + (size_t)(qrow0 + (lane >> 4) + 4 * i) * 1024 + h * 128 + (lane & 15) * 8);
.Lpf_skip:
	v_mov_b32_e32 v251, v222
	v_mov_b32_e32 v252, v223
	s_nop 1
	v_permlane16_swap_b32_e32 v251, v222
	v_permlane16_swap_b32_e32 v252, v223
	v_add_f32_e32 v222, v222, v251
	v_add_f32_e32 v223, v223, v252
	v_mov_b32_e32 v251, v222
	v_mov_b32_e32 v252, v223
	s_nop 1
	v_permlane32_swap_b32_e32 v251, v222
	v_permlane32_swap_b32_e32 v252, v223
	v_add_f32_e32 v222, v222, v251
	v_add_f32_e32 v223, v223, v252
	v_and_b32_e32 v251, 16, v220
	v_cmp_ne_u32_e32 vcc, 0, v251
	v_cndmask_b32_e32 v88, v222, v223, vcc
	s_nop 7
	v_permlane16_swap_b32_e32 v64, v68
	v_permlane16_swap_b32_e32 v65, v69
	v_permlane16_swap_b32_e32 v66, v70
	v_permlane16_swap_b32_e32 v67, v71
	v_permlane16_swap_b32_e32 v72, v76
	v_permlane16_swap_b32_e32 v73, v77
	v_permlane16_swap_b32_e32 v74, v78
	v_permlane16_swap_b32_e32 v75, v79
	v_permlane16_swap_b32_e32 v48, v52
	v_permlane16_swap_b32_e32 v49, v53
	v_permlane16_swap_b32_e32 v50, v54
	v_permlane16_swap_b32_e32 v51, v55
	v_permlane16_swap_b32_e32 v56, v60
	v_permlane16_swap_b32_e32 v57, v61
	v_permlane16_swap_b32_e32 v58, v62
	v_permlane16_swap_b32_e32 v59, v63
	v_permlane16_swap_b32_e32 v32, v36
	v_permlane16_swap_b32_e32 v33, v37
	v_permlane16_swap_b32_e32 v34, v38
	v_permlane16_swap_b32_e32 v35, v39
	v_permlane16_swap_b32_e32 v40, v44
	v_permlane16_swap_b32_e32 v41, v45
	v_permlane16_swap_b32_e32 v42, v46
	v_permlane16_swap_b32_e32 v43, v47
	v_permlane16_swap_b32_e32 v16, v20
	v_permlane16_swap_b32_e32 v17, v21
	v_permlane16_swap_b32_e32 v18, v22
	v_permlane16_swap_b32_e32 v19, v23
	v_permlane16_swap_b32_e32 v24, v28
	v_permlane16_swap_b32_e32 v25, v29
	v_permlane16_swap_b32_e32 v26, v30
	v_permlane16_swap_b32_e32 v27, v31
	v_permlane32_swap_b32_e32 v64, v68
	v_permlane32_swap_b32_e32 v65, v69
	v_permlane32_swap_b32_e32 v66, v70
	v_permlane32_swap_b32_e32 v67, v71
	v_permlane32_swap_b32_e32 v72, v76
	v_permlane32_swap_b32_e32 v73, v77
	v_permlane32_swap_b32_e32 v74, v78
	v_permlane32_swap_b32_e32 v75, v79
	v_permlane32_swap_b32_e32 v48, v52
	v_permlane32_swap_b32_e32 v49, v53
	v_permlane32_swap_b32_e32 v50, v54
	v_permlane32_swap_b32_e32 v51, v55
	v_permlane32_swap_b32_e32 v56, v60
	v_permlane32_swap_b32_e32 v57, v61
	v_permlane32_swap_b32_e32 v58, v62
	v_permlane32_swap_b32_e32 v59, v63
	v_permlane32_swap_b32_e32 v32, v36
	v_permlane32_swap_b32_e32 v33, v37
	v_permlane32_swap_b32_e32 v34, v38
	v_permlane32_swap_b32_e32 v35, v39
	v_permlane32_swap_b32_e32 v40, v44
	v_permlane32_swap_b32_e32 v41, v45
	v_permlane32_swap_b32_e32 v42, v46
	v_permlane32_swap_b32_e32 v43, v47
	v_permlane32_swap_b32_e32 v16, v20
	v_permlane32_swap_b32_e32 v17, v21
	v_permlane32_swap_b32_e32 v18, v22
	v_permlane32_swap_b32_e32 v19, v23
	v_permlane32_swap_b32_e32 v24, v28
	v_permlane32_swap_b32_e32 v25, v29
	v_permlane32_swap_b32_e32 v26, v30
	v_permlane32_swap_b32_e32 v27, v31
	v_div_scale_f32 v89, s[30:31], v88, v88, 1.0
	v_rcp_f32_e32 v90, v89
	s_nop 1
	v_fma_f32 v80, -v89, v90, 1.0
	v_fmac_f32_e32 v90, v80, v90
	v_div_scale_f32 v80, vcc, 1.0, v88, 1.0
	v_mul_f32_e32 v81, v80, v90
	v_fma_f32 v82, -v89, v81, v80
	v_fmac_f32_e32 v81, v82, v90
	s_nop 1
	v_fma_f32 v80, -v89, v81, v80
	s_nop 1
	v_div_fmas_f32 v80, v80, v90, v81
	v_div_fixup_f32 v90, v80, v88, 1.0
	v_lshl_add_u32 v80, v221, 2, s29
	s_cmp_eq_u32 s28, 1
	s_cbranch_scc1 .Lepi_m1
.Lepi_m0:
	s_add_i32 s37, s21, 0
	v_add_u32_e32 v82, s37, v150
	v_mov_b32_e32 v83, 0
	s_lshl_b32 s30, s24, 1
	s_mov_b32 s31, 0
	s_mov_b64 s[34:35], 0x2000
	s_mov_b64 s[38:39], 0x4000
	global_load_dwordx4 v[184:187], v[132:133], off
	global_load_dwordx4 v[188:191], v[132:133], off offset:32
	global_load_dwordx4 v[192:195], v[132:133], off offset:64
	global_load_dwordx4 v[196:199], v[132:133], off offset:96
	global_load_dwordx4 v[200:203], v[132:133], off offset:128
	global_load_dwordx4 v[204:207], v[132:133], off offset:160
	global_load_dwordx4 v[208:211], v[132:133], off offset:192
	global_load_dwordx4 v[212:215], v[132:133], off offset:224
	v_lshlrev_b64 v[92:93], 11, v[82:83]
	v_lshlrev_b64 v[94:95], 12, v[82:83]
	v_lshl_add_u64 v[92:93], v[92:93], 0, s[30:31]
	v_lshl_add_u64 v[94:95], v[94:95], 0, s[30:31]
	v_lshl_add_u64 v[140:141], v[134:135], 0, v[92:93]
	v_lshl_add_u64 v[240:241], v[138:139], 0, v[94:95]
	v_lshl_add_u64 v[142:143], v[140:141], 0, s[34:35]
	v_lshl_add_u64 v[242:243], v[240:241], 0, s[38:39]
	v_lshl_add_u64 v[144:145], v[142:143], 0, s[34:35]
	v_lshl_add_u64 v[244:245], v[242:243], 0, s[38:39]
	v_lshl_add_u64 v[146:147], v[144:145], 0, s[34:35]
	v_lshl_add_u64 v[222:223], v[244:245], 0, s[38:39]
	global_load_dwordx4 v[224:227], v[140:141], off
	global_load_dwordx4 v[228:231], v[142:143], off
	global_load_dwordx4 v[232:235], v[144:145], off
	global_load_dwordx4 v[236:239], v[146:147], off
	v_mov_b32_e32 v91, v90
	v_mul_f32_e32 v92, v32, v91
	v_mul_f32_e32 v93, v33, v91
	ds_write2st64_b32 v80, v92, v93 offset0:0 offset1:1
	v_mul_f32_e32 v94, v34, v91
	v_mul_f32_e32 v95, v35, v91
	ds_write2st64_b32 v80, v94, v95 offset0:2 offset1:3
	v_mul_f32_e32 v92, v36, v91
	v_mul_f32_e32 v93, v37, v91
	ds_write2st64_b32 v80, v92, v93 offset0:4 offset1:5
	v_mul_f32_e32 v94, v38, v91
	v_mul_f32_e32 v95, v39, v91
	ds_write2st64_b32 v80, v94, v95 offset0:6 offset1:7
	v_mul_f32_e32 v92, v40, v91
	v_mul_f32_e32 v93, v41, v91
	ds_write2st64_b32 v80, v92, v93 offset0:8 offset1:9
	v_mul_f32_e32 v94, v42, v91
	v_mul_f32_e32 v95, v43, v91
	ds_write2st64_b32 v80, v94, v95 offset0:10 offset1:11
	v_mul_f32_e32 v92, v44, v91
	v_mul_f32_e32 v93, v45, v91
	ds_write2st64_b32 v80, v92, v93 offset0:12 offset1:13
	v_mul_f32_e32 v94, v46, v91
	v_mul_f32_e32 v95, v47, v91
	ds_write2st64_b32 v80, v94, v95 offset0:14 offset1:15
	v_mul_f32_e32 v92, v16, v91
	v_mul_f32_e32 v93, v17, v91
	ds_write2st64_b32 v80, v92, v93 offset0:16 offset1:17
	v_mul_f32_e32 v94, v18, v91
	v_mul_f32_e32 v95, v19, v91
	ds_write2st64_b32 v80, v94, v95 offset0:18 offset1:19
	v_mul_f32_e32 v92, v20, v91
	v_mul_f32_e32 v93, v21, v91
	ds_write2st64_b32 v80, v92, v93 offset0:20 offset1:21
	v_mul_f32_e32 v94, v22, v91
	v_mul_f32_e32 v95, v23, v91
	ds_write2st64_b32 v80, v94, v95 offset0:22 offset1:23
	v_mul_f32_e32 v92, v24, v91
	v_mul_f32_e32 v93, v25, v91
	ds_write2st64_b32 v80, v92, v93 offset0:24 offset1:25
	v_mul_f32_e32 v94, v26, v91
	v_mul_f32_e32 v95, v27, v91
	ds_write2st64_b32 v80, v94, v95 offset0:26 offset1:27
	v_mul_f32_e32 v92, v28, v91
	v_mul_f32_e32 v93, v29, v91
	ds_write2st64_b32 v80, v92, v93 offset0:28 offset1:29
	v_mul_f32_e32 v94, v30, v91
	v_mul_f32_e32 v95, v31, v91
	ds_write2st64_b32 v80, v94, v95 offset0:30 offset1:31
	v_lshl_add_u32 v81, v149, 3, v155
	v_add_u32_e32 v81, s29, v81
	v_lshl_add_u32 v84, v153, 4, v137
	v_add_u32_e32 v84, s29, v84
	s_lshr_b32 s36, s29, 5
	s_add_i32 s36, s36, 0x20000
	v_lshl_add_u32 v85, v148, 2, s36
	s_waitcnt lgkmcnt(0)
	s_barrier
; #define LAS __attribute__((address_space(3)))
; __device__ __forceinline__ unsigned cvtpk(float lo, float hi) { f32x2 v = {lo, hi}; bf16x2_t b = __builtin_convertvector(v, bf16x2_t); return __builtin_bit_cast(unsigned, b); }
; __device__ __forceinline__ void attn_unit(unsigned char* ws, const float* sub_g, LAS unsigned char* lds, int h, int qb, float negM, float lam) {
;     ...
;     if (map == 0) {
;         float ss = 0.f;
; #pragma unroll
;         for (int b = 0; b < 4; ++b)
; #pragma unroll
;             for (int r = 0; r < 16; ++r) { const float v = o[b][r] * inv - xw[(b * 16 + r) * 64 + lane]; o[b][r] = v; ss += v * v; }
;         ss += __shfl_xor(ss, 32);
;         const float rs = __builtin_amdgcn_rsqf(ss * (1.0f / VD) + EPS) * (1.0f - LAM_INIT);
;         LAS unsigned char* stg = (LAS unsigned char*)xw;
; #pragma unroll
;         for (int b = 0; b < 4; ++b)
; #pragma unroll
;             for (int r4 = 0; r4 < 4; ++r4) {
;                 const int dv = 32 * b + 8 * r4 + 4 * hi;
;                 const f32x4 sg = *(const f32x4*)(sub_g + dv);
;                 u32x2 w; w.x = cvtpk(o[b][4 * r4 + 0] * rs * sg[0], o[b][4 * r4 + 1] * rs * sg[1]); w.y = cvtpk(o[b][4 * r4 + 2] * rs * sg[2], o[b][4 * r4 + 3] * rs * sg[3]);
;                 *(LAS u32x2*)(stg + r32 * 272 + dv * 2) = w;
;             }
	ds_read2st64_b32 v[96:97], v80 offset0:32 offset1:33
	ds_read2st64_b32 v[98:99], v80 offset0:34 offset1:35
	ds_read2st64_b32 v[100:101], v80 offset0:36 offset1:37
	ds_read2st64_b32 v[102:103], v80 offset0:38 offset1:39
	ds_read2st64_b32 v[104:105], v80 offset0:40 offset1:41
	ds_read2st64_b32 v[106:107], v80 offset0:42 offset1:43
	ds_read2st64_b32 v[108:109], v80 offset0:44 offset1:45
	ds_read2st64_b32 v[110:111], v80 offset0:46 offset1:47
	s_waitcnt lgkmcnt(7)
	v_fma_f32 v64, v64, v91, -v96
	v_mul_f32_e32 v86, v64, v64
	v_fma_f32 v65, v65, v91, -v97
	v_mul_f32_e32 v87, v65, v65
	s_waitcnt lgkmcnt(6)
	v_fma_f32 v66, v66, v91, -v98
	v_fmac_f32_e32 v86, v66, v66
	v_fma_f32 v67, v67, v91, -v99
	v_fmac_f32_e32 v87, v67, v67
	s_waitcnt lgkmcnt(5)
	v_fma_f32 v68, v68, v91, -v100
	v_fmac_f32_e32 v86, v68, v68
	v_fma_f32 v69, v69, v91, -v101
	v_fmac_f32_e32 v87, v69, v69
	s_waitcnt lgkmcnt(4)
	v_fma_f32 v70, v70, v91, -v102
	v_fmac_f32_e32 v86, v70, v70
	v_fma_f32 v71, v71, v91, -v103
	v_fmac_f32_e32 v87, v71, v71
	ds_read2st64_b32 v[4:5], v80 offset0:48 offset1:49
	ds_read2st64_b32 v[6:7], v80 offset0:50 offset1:51
	ds_read2st64_b32 v[8:9], v80 offset0:52 offset1:53
	ds_read2st64_b32 v[10:11], v80 offset0:54 offset1:55
	ds_read2st64_b32 v[12:13], v80 offset0:56 offset1:57
	ds_read2st64_b32 v[14:15], v80 offset0:58 offset1:59
	ds_read2st64_b32 v[216:217], v80 offset0:60 offset1:61
	ds_read2st64_b32 v[218:219], v80 offset0:62 offset1:63
	s_waitcnt lgkmcnt(11)
	v_fma_f32 v72, v72, v91, -v104
	v_fmac_f32_e32 v86, v72, v72
	v_fma_f32 v73, v73, v91, -v105
	v_fmac_f32_e32 v87, v73, v73
	s_waitcnt lgkmcnt(10)
	v_fma_f32 v74, v74, v91, -v106
	v_fmac_f32_e32 v86, v74, v74
	v_fma_f32 v75, v75, v91, -v107
	v_fmac_f32_e32 v87, v75, v75
	s_waitcnt lgkmcnt(9)
	v_fma_f32 v76, v76, v91, -v108
	v_fmac_f32_e32 v86, v76, v76
	v_fma_f32 v77, v77, v91, -v109
	v_fmac_f32_e32 v87, v77, v77
	s_waitcnt lgkmcnt(8)
	v_fma_f32 v78, v78, v91, -v110
	v_fmac_f32_e32 v86, v78, v78
	v_fma_f32 v79, v79, v91, -v111
	v_fmac_f32_e32 v87, v79, v79
	s_waitcnt lgkmcnt(7)
	v_fma_f32 v48, v48, v91, -v4
	v_fmac_f32_e32 v86, v48, v48
	v_fma_f32 v49, v49, v91, -v5
	v_fmac_f32_e32 v87, v49, v49
	s_waitcnt lgkmcnt(6)
	v_fma_f32 v50, v50, v91, -v6
	v_fmac_f32_e32 v86, v50, v50
	v_fma_f32 v51, v51, v91, -v7
	v_fmac_f32_e32 v87, v51, v51
	s_waitcnt lgkmcnt(5)
	v_fma_f32 v52, v52, v91, -v8
	v_fmac_f32_e32 v86, v52, v52
	v_fma_f32 v53, v53, v91, -v9
	v_fmac_f32_e32 v87, v53, v53
	s_waitcnt lgkmcnt(4)
	v_fma_f32 v54, v54, v91, -v10
	v_fmac_f32_e32 v86, v54, v54
	v_fma_f32 v55, v55, v91, -v11
	v_fmac_f32_e32 v87, v55, v55
	s_waitcnt lgkmcnt(3)
	v_fma_f32 v56, v56, v91, -v12
	v_fmac_f32_e32 v86, v56, v56
	v_fma_f32 v57, v57, v91, -v13
	v_fmac_f32_e32 v87, v57, v57
	s_waitcnt lgkmcnt(2)
	v_fma_f32 v58, v58, v91, -v14
	v_fmac_f32_e32 v86, v58, v58
	v_fma_f32 v59, v59, v91, -v15
	v_fmac_f32_e32 v87, v59, v59
	s_waitcnt lgkmcnt(1)
	v_fma_f32 v60, v60, v91, -v216
	v_fmac_f32_e32 v86, v60, v60
	v_fma_f32 v61, v61, v91, -v217
	v_fmac_f32_e32 v87, v61, v61
	s_waitcnt lgkmcnt(0)
	v_fma_f32 v62, v62, v91, -v218
	v_fmac_f32_e32 v86, v62, v62
	v_fma_f32 v63, v63, v91, -v219
	v_fmac_f32_e32 v87, v63, v63
	v_add_f32_e32 v86, v86, v87
	v_mov_b32_e32 v92, v86
	s_nop 1
	v_permlane32_swap_b32_e32 v92, v86
	v_add_f32_e32 v86, v86, v92
	ds_write_b32 v85, v86
	s_waitcnt lgkmcnt(0)
	s_barrier
	ds_read_b32 v92, v85 offset:256
	s_waitcnt lgkmcnt(0)
	v_add_f32_e32 v86, v86, v92
	v_fmamk_f32 v86, v86, 0x3c000000, v182
	v_rsq_f32_e32 v86, v86
	s_nop 0
	v_mul_f32_e32 v86, 0x3f4ccccd, v86
	s_waitcnt vmcnt(4)
	v_mul_f32_e32 v64, v64, v86
	v_mul_f32_e32 v65, v65, v86
	v_mul_f32_e32 v66, v66, v86
	v_mul_f32_e32 v67, v67, v86
	v_mul_f32_e32 v64, v64, v184
	v_mul_f32_e32 v65, v65, v185
	v_mul_f32_e32 v66, v66, v186
	v_mul_f32_e32 v67, v67, v187
	v_cvt_pk_bf16_f32 v92, v64, v65
	v_cvt_pk_bf16_f32 v93, v66, v67
	ds_write_b64 v81, v[92:93] offset:0
	v_mul_f32_e32 v68, v68, v86
	v_mul_f32_e32 v69, v69, v86
	v_mul_f32_e32 v70, v70, v86
	v_mul_f32_e32 v71, v71, v86
	v_mul_f32_e32 v68, v68, v188
	v_mul_f32_e32 v69, v69, v189
	v_mul_f32_e32 v70, v70, v190
	v_mul_f32_e32 v71, v71, v191
	v_cvt_pk_bf16_f32 v94, v68, v69
	v_cvt_pk_bf16_f32 v95, v70, v71
	ds_write_b64 v81, v[94:95] offset:16
	v_mul_f32_e32 v72, v72, v86
	v_mul_f32_e32 v73, v73, v86
	v_mul_f32_e32 v74, v74, v86
	v_mul_f32_e32 v75, v75, v86
	v_mul_f32_e32 v72, v72, v192
	v_mul_f32_e32 v73, v73, v193
	v_mul_f32_e32 v74, v74, v194
	v_mul_f32_e32 v75, v75, v195
	v_cvt_pk_bf16_f32 v92, v72, v73
	v_cvt_pk_bf16_f32 v93, v74, v75
	ds_write_b64 v81, v[92:93] offset:32
	v_mul_f32_e32 v76, v76, v86
	v_mul_f32_e32 v77, v77, v86
	v_mul_f32_e32 v78, v78, v86
	v_mul_f32_e32 v79, v79, v86
	v_mul_f32_e32 v76, v76, v196
	v_mul_f32_e32 v77, v77, v197
	v_mul_f32_e32 v78, v78, v198
	v_mul_f32_e32 v79, v79, v199
	v_cvt_pk_bf16_f32 v94, v76, v77
	v_cvt_pk_bf16_f32 v95, v78, v79
	ds_write_b64 v81, v[94:95] offset:48
	v_mul_f32_e32 v48, v48, v86
	v_mul_f32_e32 v49, v49, v86
	v_mul_f32_e32 v50, v50, v86
	v_mul_f32_e32 v51, v51, v86
	v_mul_f32_e32 v48, v48, v200
	v_mul_f32_e32 v49, v49, v201
	v_mul_f32_e32 v50, v50, v202
	v_mul_f32_e32 v51, v51, v203
	v_cvt_pk_bf16_f32 v92, v48, v49
	v_cvt_pk_bf16_f32 v93, v50, v51
	ds_write_b64 v81, v[92:93] offset:64
	v_mul_f32_e32 v52, v52, v86
	v_mul_f32_e32 v53, v53, v86
	v_mul_f32_e32 v54, v54, v86
	v_mul_f32_e32 v55, v55, v86
	v_mul_f32_e32 v52, v52, v204
	v_mul_f32_e32 v53, v53, v205
	v_mul_f32_e32 v54, v54, v206
	v_mul_f32_e32 v55, v55, v207
	v_cvt_pk_bf16_f32 v94, v52, v53
	v_cvt_pk_bf16_f32 v95, v54, v55
	ds_write_b64 v81, v[94:95] offset:80
	v_mul_f32_e32 v56, v56, v86
	v_mul_f32_e32 v57, v57, v86
	v_mul_f32_e32 v58, v58, v86
	v_mul_f32_e32 v59, v59, v86
	v_mul_f32_e32 v56, v56, v208
	v_mul_f32_e32 v57, v57, v209
	v_mul_f32_e32 v58, v58, v210
	v_mul_f32_e32 v59, v59, v211
	v_cvt_pk_bf16_f32 v92, v56, v57
	v_cvt_pk_bf16_f32 v93, v58, v59
	ds_write_b64 v81, v[92:93] offset:96
	v_mul_f32_e32 v60, v60, v86
	v_mul_f32_e32 v61, v61, v86
	v_mul_f32_e32 v62, v62, v86
	v_mul_f32_e32 v63, v63, v86
	v_mul_f32_e32 v60, v60, v212
	v_mul_f32_e32 v61, v61, v213
	v_mul_f32_e32 v62, v62, v214
	v_mul_f32_e32 v63, v63, v215
	v_cvt_pk_bf16_f32 v94, v60, v61
	v_cvt_pk_bf16_f32 v95, v62, v63
	ds_write_b64 v81, v[94:95] offset:112
	s_waitcnt lgkmcnt(0)
	s_barrier
; #define LAS __attribute__((address_space(3)))
; __device__ __forceinline__ unsigned cvtpk(float lo, float hi) { f32x2 v = {lo, hi}; bf16x2_t b = __builtin_convertvector(v, bf16x2_t); return __builtin_bit_cast(unsigned, b); }
; __device__ __forceinline__ void attn_unit(unsigned char* ws, const float* sub_g, LAS unsigned char* lds, int h, int qb, float negM, float lam) {
;     ...
;         asm volatile("s_waitcnt lgkmcnt(0)" ::: "memory");
;         const bf16_t* GA = (const bf16_t*)(ws + WS_GA); bf16_t* MIX = (bf16_t*)(ws + WS_MIX);
;         u32x4 gvs[8];
; #pragma unroll
;         for (int i = 0; i < 8; ++i) gvs[i] = *(const u32x4*)(GA + (size_t)(qrow0 + (lane >> 4) + 4 * i) * 1024 + h * 128 + (lane & 15) * 8);
; #pragma unroll
;         for (int i = 0; i < 8; ++i) {
;             const int q = (lane >> 4) + 4 * i, ch = lane & 15;
;             const u32x4 ov = *(const LAS u32x4*)(stg + q * 272 + ch * 16);
;             const size_t tok = (size_t)(qrow0 + q);
;             const u32x4 gv = gvs[i];
;             u32x4 w;
;             w.x = cvtpk(bf_lo(ov.x) * bf_lo(gv.x), bf_hi(ov.x) * bf_hi(gv.x)); w.y = cvtpk(bf_lo(ov.y) * bf_lo(gv.y), bf_hi(ov.y) * bf_hi(gv.y));
;             w.z = cvtpk(bf_lo(ov.z) * bf_lo(gv.z), bf_hi(ov.z) * bf_hi(gv.z)); w.w = cvtpk(bf_lo(ov.w) * bf_lo(gv.w), bf_hi(ov.w) * bf_hi(gv.w));
;             *(u32x4*)(MIX + tok * DM + h * 128 + ch * 8) = w;
;         }
	ds_read_b128 v[96:99], v84 offset:0
	ds_read_b128 v[100:103], v84 offset:1088
	ds_read_b128 v[104:107], v84 offset:2176
	ds_read_b128 v[108:111], v84 offset:3264
	s_waitcnt vmcnt(0)
	s_waitcnt lgkmcnt(3)
	v_lshlrev_b32_e32 v92, 16, v96
	v_and_b32_e32 v93, 0xffff0000, v96
	v_lshlrev_b32_e32 v94, 16, v224
	v_and_b32_e32 v95, 0xffff0000, v224
	v_mul_f32_e32 v92, v92, v94
	v_mul_f32_e32 v93, v93, v95
	v_cvt_pk_bf16_f32 v16, v92, v93
	v_lshlrev_b32_e32 v92, 16, v97
	v_and_b32_e32 v93, 0xffff0000, v97
	v_lshlrev_b32_e32 v94, 16, v225
	v_and_b32_e32 v95, 0xffff0000, v225
	v_mul_f32_e32 v92, v92, v94
	v_mul_f32_e32 v93, v93, v95
	v_cvt_pk_bf16_f32 v17, v92, v93
	v_lshlrev_b32_e32 v92, 16, v98
	v_and_b32_e32 v93, 0xffff0000, v98
	v_lshlrev_b32_e32 v94, 16, v226
	v_and_b32_e32 v95, 0xffff0000, v226
	v_mul_f32_e32 v92, v92, v94
	v_mul_f32_e32 v93, v93, v95
	v_cvt_pk_bf16_f32 v18, v92, v93
	v_lshlrev_b32_e32 v92, 16, v99
	v_and_b32_e32 v93, 0xffff0000, v99
	v_lshlrev_b32_e32 v94, 16, v227
	v_and_b32_e32 v95, 0xffff0000, v227
	v_mul_f32_e32 v92, v92, v94
	v_mul_f32_e32 v93, v93, v95
	v_cvt_pk_bf16_f32 v19, v92, v93
	global_store_dwordx4 v[240:241], v[16:19], off
	s_waitcnt lgkmcnt(2)
	v_lshlrev_b32_e32 v92, 16, v100
	v_and_b32_e32 v93, 0xffff0000, v100
	v_lshlrev_b32_e32 v94, 16, v228
	v_and_b32_e32 v95, 0xffff0000, v228
	v_mul_f32_e32 v92, v92, v94
	v_mul_f32_e32 v93, v93, v95
	v_cvt_pk_bf16_f32 v20, v92, v93
	v_lshlrev_b32_e32 v92, 16, v101
	v_and_b32_e32 v93, 0xffff0000, v101
	v_lshlrev_b32_e32 v94, 16, v229
	v_and_b32_e32 v95, 0xffff0000, v229
	v_mul_f32_e32 v92, v92, v94
	v_mul_f32_e32 v93, v93, v95
	v_cvt_pk_bf16_f32 v21, v92, v93
	v_lshlrev_b32_e32 v92, 16, v102
	v_and_b32_e32 v93, 0xffff0000, v102
	v_lshlrev_b32_e32 v94, 16, v230
	v_and_b32_e32 v95, 0xffff0000, v230
	v_mul_f32_e32 v92, v92, v94
	v_mul_f32_e32 v93, v93, v95
	v_cvt_pk_bf16_f32 v22, v92, v93
	v_lshlrev_b32_e32 v92, 16, v103
	v_and_b32_e32 v93, 0xffff0000, v103
	v_lshlrev_b32_e32 v94, 16, v231
	v_and_b32_e32 v95, 0xffff0000, v231
	v_mul_f32_e32 v92, v92, v94
	v_mul_f32_e32 v93, v93, v95
	v_cvt_pk_bf16_f32 v23, v92, v93
	global_store_dwordx4 v[242:243], v[20:23], off
	s_waitcnt lgkmcnt(1)
	v_lshlrev_b32_e32 v92, 16, v104
	v_and_b32_e32 v93, 0xffff0000, v104
	v_lshlrev_b32_e32 v94, 16, v232
	v_and_b32_e32 v95, 0xffff0000, v232
	v_mul_f32_e32 v92, v92, v94
	v_mul_f32_e32 v93, v93, v95
	v_cvt_pk_bf16_f32 v24, v92, v93
	v_lshlrev_b32_e32 v92, 16, v105
	v_and_b32_e32 v93, 0xffff0000, v105
	v_lshlrev_b32_e32 v94, 16, v233
	v_and_b32_e32 v95, 0xffff0000, v233
	v_mul_f32_e32 v92, v92, v94
	v_mul_f32_e32 v93, v93, v95
	v_cvt_pk_bf16_f32 v25, v92, v93
	v_lshlrev_b32_e32 v92, 16, v106
	v_and_b32_e32 v93, 0xffff0000, v106
	v_lshlrev_b32_e32 v94, 16, v234
	v_and_b32_e32 v95, 0xffff0000, v234
	v_mul_f32_e32 v92, v92, v94
	v_mul_f32_e32 v93, v93, v95
	v_cvt_pk_bf16_f32 v26, v92, v93
	v_lshlrev_b32_e32 v92, 16, v107
	v_and_b32_e32 v93, 0xffff0000, v107
	v_lshlrev_b32_e32 v94, 16, v235
	v_and_b32_e32 v95, 0xffff0000, v235
	v_mul_f32_e32 v92, v92, v94
	v_mul_f32_e32 v93, v93, v95
	v_cvt_pk_bf16_f32 v27, v92, v93
	global_store_dwordx4 v[244:245], v[24:27], off
	s_waitcnt lgkmcnt(0)
	v_lshlrev_b32_e32 v92, 16, v108
	v_and_b32_e32 v93, 0xffff0000, v108
	v_lshlrev_b32_e32 v94, 16, v236
	v_and_b32_e32 v95, 0xffff0000, v236
	v_mul_f32_e32 v92, v92, v94
	v_mul_f32_e32 v93, v93, v95
	v_cvt_pk_bf16_f32 v28, v92, v93
	v_lshlrev_b32_e32 v92, 16, v109
	v_and_b32_e32 v93, 0xffff0000, v109
	v_lshlrev_b32_e32 v94, 16, v237
	v_and_b32_e32 v95, 0xffff0000, v237
	v_mul_f32_e32 v92, v92, v94
	v_mul_f32_e32 v93, v93, v95
	v_cvt_pk_bf16_f32 v29, v92, v93
	v_lshlrev_b32_e32 v92, 16, v110
	v_and_b32_e32 v93, 0xffff0000, v110
	v_lshlrev_b32_e32 v94, 16, v238
	v_and_b32_e32 v95, 0xffff0000, v238
	v_mul_f32_e32 v92, v92, v94
	v_mul_f32_e32 v93, v93, v95
	v_cvt_pk_bf16_f32 v30, v92, v93
	v_lshlrev_b32_e32 v92, 16, v111
	v_and_b32_e32 v93, 0xffff0000, v111
	v_lshlrev_b32_e32 v94, 16, v239
	v_and_b32_e32 v95, 0xffff0000, v239
	v_mul_f32_e32 v92, v92, v94
	v_mul_f32_e32 v93, v93, v95
	v_cvt_pk_bf16_f32 v31, v92, v93
	global_store_dwordx4 v[222:223], v[28:31], off
	s_branch .LBB0_829
.Lepi_m1:
	s_add_i32 s37, s21, 16
	v_add_u32_e32 v82, s37, v150
	v_mov_b32_e32 v83, 0
	s_lshl_b32 s30, s24, 1
	s_mov_b32 s31, 0
	s_mov_b64 s[34:35], 0x2000
	s_mov_b64 s[38:39], 0x4000
	global_load_dwordx4 v[184:187], v[132:133], off offset:256
	global_load_dwordx4 v[188:191], v[132:133], off offset:288
	global_load_dwordx4 v[192:195], v[132:133], off offset:320
	global_load_dwordx4 v[196:199], v[132:133], off offset:352
	global_load_dwordx4 v[200:203], v[132:133], off offset:384
	global_load_dwordx4 v[204:207], v[132:133], off offset:416
	global_load_dwordx4 v[208:211], v[132:133], off offset:448
	global_load_dwordx4 v[212:215], v[132:133], off offset:480
	v_lshlrev_b64 v[92:93], 11, v[82:83]
	v_lshlrev_b64 v[94:95], 12, v[82:83]
	v_lshl_add_u64 v[92:93], v[92:93], 0, s[30:31]
	v_lshl_add_u64 v[94:95], v[94:95], 0, s[30:31]
	v_lshl_add_u64 v[140:141], v[134:135], 0, v[92:93]
	v_lshl_add_u64 v[240:241], v[138:139], 0, v[94:95]
	v_lshl_add_u64 v[142:143], v[140:141], 0, s[34:35]
	v_lshl_add_u64 v[242:243], v[240:241], 0, s[38:39]
	v_lshl_add_u64 v[144:145], v[142:143], 0, s[34:35]
	v_lshl_add_u64 v[244:245], v[242:243], 0, s[38:39]
	v_lshl_add_u64 v[146:147], v[144:145], 0, s[34:35]
	v_lshl_add_u64 v[222:223], v[244:245], 0, s[38:39]
	global_load_dwordx4 v[224:227], v[140:141], off
	global_load_dwordx4 v[228:231], v[142:143], off
	global_load_dwordx4 v[232:235], v[144:145], off
	global_load_dwordx4 v[236:239], v[146:147], off
	v_mul_f32_e32 v91, v129, v90
; __device__ __forceinline__ void attn_unit(unsigned char* ws, const float* sub_g, LAS unsigned char* lds, int h, int qb, float negM, float lam) {
;     ...
;     if (map == 1) {
;         const float f = inv * lam;
; #pragma unroll
;         for (int b = 0; b < 4; ++b)
; #pragma unroll
;             for (int r = 0; r < 16; ++r) xw[(b * 16 + r) * 64 + lane] = o[b][r] * f;
;     }
;     __syncthreads();
;     if (map == 0) {
;         float ss = 0.f;
; #pragma unroll
;         for (int b = 0; b < 4; ++b)
; #pragma unroll
;             for (int r = 0; r < 16; ++r) { const float v = o[b][r] * inv - xw[(b * 16 + r) * 64 + lane]; o[b][r] = v; ss += v * v; }
;         ss += __shfl_xor(ss, 32);
	v_mul_f32_e32 v92, v64, v91
	v_mul_f32_e32 v93, v65, v91
	ds_write2st64_b32 v80, v92, v93 offset0:32 offset1:33
	v_mul_f32_e32 v94, v66, v91
	v_mul_f32_e32 v95, v67, v91
	ds_write2st64_b32 v80, v94, v95 offset0:34 offset1:35
	v_mul_f32_e32 v92, v68, v91
	v_mul_f32_e32 v93, v69, v91
	ds_write2st64_b32 v80, v92, v93 offset0:36 offset1:37
	v_mul_f32_e32 v94, v70, v91
	v_mul_f32_e32 v95, v71, v91
	ds_write2st64_b32 v80, v94, v95 offset0:38 offset1:39
	v_mul_f32_e32 v92, v72, v91
	v_mul_f32_e32 v93, v73, v91
	ds_write2st64_b32 v80, v92, v93 offset0:40 offset1:41
	v_mul_f32_e32 v94, v74, v91
	v_mul_f32_e32 v95, v75, v91
	ds_write2st64_b32 v80, v94, v95 offset0:42 offset1:43
	v_mul_f32_e32 v92, v76, v91
	v_mul_f32_e32 v93, v77, v91
	ds_write2st64_b32 v80, v92, v93 offset0:44 offset1:45
	v_mul_f32_e32 v94, v78, v91
	v_mul_f32_e32 v95, v79, v91
	ds_write2st64_b32 v80, v94, v95 offset0:46 offset1:47
	v_mul_f32_e32 v92, v48, v91
	v_mul_f32_e32 v93, v49, v91
	ds_write2st64_b32 v80, v92, v93 offset0:48 offset1:49
	v_mul_f32_e32 v94, v50, v91
	v_mul_f32_e32 v95, v51, v91
	ds_write2st64_b32 v80, v94, v95 offset0:50 offset1:51
	v_mul_f32_e32 v92, v52, v91
	v_mul_f32_e32 v93, v53, v91
	ds_write2st64_b32 v80, v92, v93 offset0:52 offset1:53
	v_mul_f32_e32 v94, v54, v91
	v_mul_f32_e32 v95, v55, v91
	ds_write2st64_b32 v80, v94, v95 offset0:54 offset1:55
	v_mul_f32_e32 v92, v56, v91
	v_mul_f32_e32 v93, v57, v91
	ds_write2st64_b32 v80, v92, v93 offset0:56 offset1:57
	v_mul_f32_e32 v94, v58, v91
	v_mul_f32_e32 v95, v59, v91
	ds_write2st64_b32 v80, v94, v95 offset0:58 offset1:59
	v_mul_f32_e32 v92, v60, v91
	v_mul_f32_e32 v93, v61, v91
	ds_write2st64_b32 v80, v92, v93 offset0:60 offset1:61
	v_mul_f32_e32 v94, v62, v91
	v_mul_f32_e32 v95, v63, v91
	ds_write2st64_b32 v80, v94, v95 offset0:62 offset1:63
	v_lshl_add_u32 v81, v149, 3, v155
	v_add_u32_e32 v81, s29, v81
	v_lshl_add_u32 v84, v153, 4, v137
	v_add_u32_e32 v84, s29, v84
	s_lshr_b32 s36, s29, 5
	s_add_i32 s36, s36, 0x20000
	v_lshl_add_u32 v85, v148, 2, s36
	s_waitcnt lgkmcnt(0)
	s_barrier
	ds_read2st64_b32 v[96:97], v80 offset0:0 offset1:1
	ds_read2st64_b32 v[98:99], v80 offset0:2 offset1:3
	ds_read2st64_b32 v[100:101], v80 offset0:4 offset1:5
	ds_read2st64_b32 v[102:103], v80 offset0:6 offset1:7
	ds_read2st64_b32 v[104:105], v80 offset0:8 offset1:9
	ds_read2st64_b32 v[106:107], v80 offset0:10 offset1:11
	ds_read2st64_b32 v[108:109], v80 offset0:12 offset1:13
	ds_read2st64_b32 v[110:111], v80 offset0:14 offset1:15
	s_waitcnt lgkmcnt(7)
	v_fma_f32 v32, -v32, v91, v96
	v_mul_f32_e32 v86, v32, v32
	v_fma_f32 v33, -v33, v91, v97
	v_mul_f32_e32 v87, v33, v33
	s_waitcnt lgkmcnt(6)
	v_fma_f32 v34, -v34, v91, v98
	v_fmac_f32_e32 v86, v34, v34
	v_fma_f32 v35, -v35, v91, v99
	v_fmac_f32_e32 v87, v35, v35
	s_waitcnt lgkmcnt(5)
	v_fma_f32 v36, -v36, v91, v100
	v_fmac_f32_e32 v86, v36, v36
	v_fma_f32 v37, -v37, v91, v101
	v_fmac_f32_e32 v87, v37, v37
	s_waitcnt lgkmcnt(4)
	v_fma_f32 v38, -v38, v91, v102
	v_fmac_f32_e32 v86, v38, v38
	v_fma_f32 v39, -v39, v91, v103
	v_fmac_f32_e32 v87, v39, v39
	ds_read2st64_b32 v[4:5], v80 offset0:16 offset1:17
	ds_read2st64_b32 v[6:7], v80 offset0:18 offset1:19
	ds_read2st64_b32 v[8:9], v80 offset0:20 offset1:21
	ds_read2st64_b32 v[10:11], v80 offset0:22 offset1:23
	ds_read2st64_b32 v[12:13], v80 offset0:24 offset1:25
	ds_read2st64_b32 v[14:15], v80 offset0:26 offset1:27
	ds_read2st64_b32 v[216:217], v80 offset0:28 offset1:29
	ds_read2st64_b32 v[218:219], v80 offset0:30 offset1:31
	s_waitcnt lgkmcnt(11)
	v_fma_f32 v40, -v40, v91, v104
	v_fmac_f32_e32 v86, v40, v40
	v_fma_f32 v41, -v41, v91, v105
	v_fmac_f32_e32 v87, v41, v41
	s_waitcnt lgkmcnt(10)
	v_fma_f32 v42, -v42, v91, v106
	v_fmac_f32_e32 v86, v42, v42
	v_fma_f32 v43, -v43, v91, v107
	v_fmac_f32_e32 v87, v43, v43
	s_waitcnt lgkmcnt(9)
	v_fma_f32 v44, -v44, v91, v108
	v_fmac_f32_e32 v86, v44, v44
	v_fma_f32 v45, -v45, v91, v109
	v_fmac_f32_e32 v87, v45, v45
	s_waitcnt lgkmcnt(8)
	v_fma_f32 v46, -v46, v91, v110
	v_fmac_f32_e32 v86, v46, v46
	v_fma_f32 v47, -v47, v91, v111
	v_fmac_f32_e32 v87, v47, v47
	s_waitcnt lgkmcnt(7)
	v_fma_f32 v16, -v16, v91, v4
	v_fmac_f32_e32 v86, v16, v16
	v_fma_f32 v17, -v17, v91, v5
	v_fmac_f32_e32 v87, v17, v17
	s_waitcnt lgkmcnt(6)
	v_fma_f32 v18, -v18, v91, v6
	v_fmac_f32_e32 v86, v18, v18
	v_fma_f32 v19, -v19, v91, v7
	v_fmac_f32_e32 v87, v19, v19
	s_waitcnt lgkmcnt(5)
	v_fma_f32 v20, -v20, v91, v8
	v_fmac_f32_e32 v86, v20, v20
	v_fma_f32 v21, -v21, v91, v9
	v_fmac_f32_e32 v87, v21, v21
	s_waitcnt lgkmcnt(4)
	v_fma_f32 v22, -v22, v91, v10
	v_fmac_f32_e32 v86, v22, v22
	v_fma_f32 v23, -v23, v91, v11
	v_fmac_f32_e32 v87, v23, v23
	s_waitcnt lgkmcnt(3)
	v_fma_f32 v24, -v24, v91, v12
	v_fmac_f32_e32 v86, v24, v24
	v_fma_f32 v25, -v25, v91, v13
	v_fmac_f32_e32 v87, v25, v25
	s_waitcnt lgkmcnt(2)
	v_fma_f32 v26, -v26, v91, v14
	v_fmac_f32_e32 v86, v26, v26
	v_fma_f32 v27, -v27, v91, v15
	v_fmac_f32_e32 v87, v27, v27
	s_waitcnt lgkmcnt(1)
	v_fma_f32 v28, -v28, v91, v216
	v_fmac_f32_e32 v86, v28, v28
	v_fma_f32 v29, -v29, v91, v217
	v_fmac_f32_e32 v87, v29, v29
	s_waitcnt lgkmcnt(0)
	v_fma_f32 v30, -v30, v91, v218
	v_fmac_f32_e32 v86, v30, v30
	v_fma_f32 v31, -v31, v91, v219
	v_fmac_f32_e32 v87, v31, v31
	v_add_f32_e32 v86, v86, v87
	v_mov_b32_e32 v92, v86
	s_nop 1
	v_permlane32_swap_b32_e32 v92, v86
	v_add_f32_e32 v86, v86, v92
	ds_write_b32 v85, v86 offset:256
	s_waitcnt lgkmcnt(0)
	s_barrier
; #define LAS __attribute__((address_space(3)))
; __device__ __forceinline__ unsigned cvtpk(float lo, float hi) { f32x2 v = {lo, hi}; bf16x2_t b = __builtin_convertvector(v, bf16x2_t); return __builtin_bit_cast(unsigned, b); }
; __device__ __forceinline__ void attn_unit(unsigned char* ws, const float* sub_g, LAS unsigned char* lds, int h, int qb, float negM, float lam) {
;     ...
;         ss += __shfl_xor(ss, 32);
;         const float rs = __builtin_amdgcn_rsqf(ss * (1.0f / VD) + EPS) * (1.0f - LAM_INIT);
;         LAS unsigned char* stg = (LAS unsigned char*)xw;
; #pragma unroll
;         for (int b = 0; b < 4; ++b)
; #pragma unroll
;             for (int r4 = 0; r4 < 4; ++r4) {
;                 const int dv = 32 * b + 8 * r4 + 4 * hi;
;                 const f32x4 sg = *(const f32x4*)(sub_g + dv);
;                 u32x2 w; w.x = cvtpk(o[b][4 * r4 + 0] * rs * sg[0], o[b][4 * r4 + 1] * rs * sg[1]); w.y = cvtpk(o[b][4 * r4 + 2] * rs * sg[2], o[b][4 * r4 + 3] * rs * sg[3]);
;                 *(LAS u32x2*)(stg + r32 * 272 + dv * 2) = w;
;             }
	ds_read_b32 v92, v85
	s_waitcnt lgkmcnt(0)
	v_add_f32_e32 v86, v86, v92
	v_fmamk_f32 v86, v86, 0x3c000000, v182
	v_rsq_f32_e32 v86, v86
	s_nop 0
	v_mul_f32_e32 v86, 0x3f4ccccd, v86
	s_waitcnt vmcnt(4)
	v_mul_f32_e32 v32, v32, v86
	v_mul_f32_e32 v33, v33, v86
	v_mul_f32_e32 v34, v34, v86
	v_mul_f32_e32 v35, v35, v86
	v_mul_f32_e32 v32, v32, v184
	v_mul_f32_e32 v33, v33, v185
	v_mul_f32_e32 v34, v34, v186
	v_mul_f32_e32 v35, v35, v187
	v_cvt_pk_bf16_f32 v92, v32, v33
	v_cvt_pk_bf16_f32 v93, v34, v35
	ds_write_b64 v81, v[92:93] offset:128
	v_mul_f32_e32 v36, v36, v86
	v_mul_f32_e32 v37, v37, v86
	v_mul_f32_e32 v38, v38, v86
	v_mul_f32_e32 v39, v39, v86
	v_mul_f32_e32 v36, v36, v188
	v_mul_f32_e32 v37, v37, v189
	v_mul_f32_e32 v38, v38, v190
	v_mul_f32_e32 v39, v39, v191
	v_cvt_pk_bf16_f32 v94, v36, v37
	v_cvt_pk_bf16_f32 v95, v38, v39
	ds_write_b64 v81, v[94:95] offset:144
	v_mul_f32_e32 v40, v40, v86
	v_mul_f32_e32 v41, v41, v86
	v_mul_f32_e32 v42, v42, v86
	v_mul_f32_e32 v43, v43, v86
	v_mul_f32_e32 v40, v40, v192
	v_mul_f32_e32 v41, v41, v193
	v_mul_f32_e32 v42, v42, v194
	v_mul_f32_e32 v43, v43, v195
	v_cvt_pk_bf16_f32 v92, v40, v41
	v_cvt_pk_bf16_f32 v93, v42, v43
	ds_write_b64 v81, v[92:93] offset:160
	v_mul_f32_e32 v44, v44, v86
	v_mul_f32_e32 v45, v45, v86
	v_mul_f32_e32 v46, v46, v86
	v_mul_f32_e32 v47, v47, v86
	v_mul_f32_e32 v44, v44, v196
	v_mul_f32_e32 v45, v45, v197
	v_mul_f32_e32 v46, v46, v198
	v_mul_f32_e32 v47, v47, v199
	v_cvt_pk_bf16_f32 v94, v44, v45
	v_cvt_pk_bf16_f32 v95, v46, v47
	ds_write_b64 v81, v[94:95] offset:176
	v_mul_f32_e32 v16, v16, v86
	v_mul_f32_e32 v17, v17, v86
	v_mul_f32_e32 v18, v18, v86
	v_mul_f32_e32 v19, v19, v86
	v_mul_f32_e32 v16, v16, v200
	v_mul_f32_e32 v17, v17, v201
	v_mul_f32_e32 v18, v18, v202
	v_mul_f32_e32 v19, v19, v203
	v_cvt_pk_bf16_f32 v92, v16, v17
	v_cvt_pk_bf16_f32 v93, v18, v19
	ds_write_b64 v81, v[92:93] offset:192
	v_mul_f32_e32 v20, v20, v86
	v_mul_f32_e32 v21, v21, v86
	v_mul_f32_e32 v22, v22, v86
	v_mul_f32_e32 v23, v23, v86
	v_mul_f32_e32 v20, v20, v204
	v_mul_f32_e32 v21, v21, v205
	v_mul_f32_e32 v22, v22, v206
	v_mul_f32_e32 v23, v23, v207
	v_cvt_pk_bf16_f32 v94, v20, v21
	v_cvt_pk_bf16_f32 v95, v22, v23
	ds_write_b64 v81, v[94:95] offset:208
	v_mul_f32_e32 v24, v24, v86
	v_mul_f32_e32 v25, v25, v86
	v_mul_f32_e32 v26, v26, v86
	v_mul_f32_e32 v27, v27, v86
	v_mul_f32_e32 v24, v24, v208
	v_mul_f32_e32 v25, v25, v209
	v_mul_f32_e32 v26, v26, v210
	v_mul_f32_e32 v27, v27, v211
	v_cvt_pk_bf16_f32 v92, v24, v25
	v_cvt_pk_bf16_f32 v93, v26, v27
	ds_write_b64 v81, v[92:93] offset:224
	v_mul_f32_e32 v28, v28, v86
	v_mul_f32_e32 v29, v29, v86
	v_mul_f32_e32 v30, v30, v86
	v_mul_f32_e32 v31, v31, v86
	v_mul_f32_e32 v28, v28, v212
	v_mul_f32_e32 v29, v29, v213
	v_mul_f32_e32 v30, v30, v214
	v_mul_f32_e32 v31, v31, v215
	v_cvt_pk_bf16_f32 v94, v28, v29
	v_cvt_pk_bf16_f32 v95, v30, v31
	ds_write_b64 v81, v[94:95] offset:240
	s_waitcnt lgkmcnt(0)
	s_barrier
; #define LAS __attribute__((address_space(3)))
; __device__ __forceinline__ unsigned cvtpk(float lo, float hi) { f32x2 v = {lo, hi}; bf16x2_t b = __builtin_convertvector(v, bf16x2_t); return __builtin_bit_cast(unsigned, b); }
; __device__ __forceinline__ void attn_unit(unsigned char* ws, const float* sub_g, LAS unsigned char* lds, int h, int qb, float negM, float lam) {
;     ...
;         asm volatile("s_waitcnt lgkmcnt(0)" ::: "memory");
;         const bf16_t* GA = (const bf16_t*)(ws + WS_GA); bf16_t* MIX = (bf16_t*)(ws + WS_MIX);
;         u32x4 gvs[8];
; #pragma unroll
;         for (int i = 0; i < 8; ++i) gvs[i] = *(const u32x4*)(GA + (size_t)(qrow0 + (lane >> 4) + 4 * i) * 1024 + h * 128 + (lane & 15) * 8);
; #pragma unroll
;         for (int i = 0; i < 8; ++i) {
;             const int q = (lane >> 4) + 4 * i, ch = lane & 15;
;             const u32x4 ov = *(const LAS u32x4*)(stg + q * 272 + ch * 16);
;             const size_t tok = (size_t)(qrow0 + q);
;             const u32x4 gv = gvs[i];
;             u32x4 w;
;             w.x = cvtpk(bf_lo(ov.x) * bf_lo(gv.x), bf_hi(ov.x) * bf_hi(gv.x)); w.y = cvtpk(bf_lo(ov.y) * bf_lo(gv.y), bf_hi(ov.y) * bf_hi(gv.y));
;             w.z = cvtpk(bf_lo(ov.z) * bf_lo(gv.z), bf_hi(ov.z) * bf_hi(gv.z)); w.w = cvtpk(bf_lo(ov.w) * bf_lo(gv.w), bf_hi(ov.w) * bf_hi(gv.w));
;             *(u32x4*)(MIX + tok * DM + h * 128 + ch * 8) = w;
;         }
	ds_read_b128 v[96:99], v84 offset:4352
	ds_read_b128 v[100:103], v84 offset:5440
	ds_read_b128 v[104:107], v84 offset:6528
	ds_read_b128 v[108:111], v84 offset:7616
	s_waitcnt vmcnt(0)
	s_waitcnt lgkmcnt(3)
	v_lshlrev_b32_e32 v92, 16, v96
	v_and_b32_e32 v93, 0xffff0000, v96
	v_lshlrev_b32_e32 v94, 16, v224
	v_and_b32_e32 v95, 0xffff0000, v224
	v_mul_f32_e32 v92, v92, v94
	v_mul_f32_e32 v93, v93, v95
	v_cvt_pk_bf16_f32 v64, v92, v93
	v_lshlrev_b32_e32 v92, 16, v97
	v_and_b32_e32 v93, 0xffff0000, v97
	v_lshlrev_b32_e32 v94, 16, v225
	v_and_b32_e32 v95, 0xffff0000, v225
	v_mul_f32_e32 v92, v92, v94
	v_mul_f32_e32 v93, v93, v95
	v_cvt_pk_bf16_f32 v65, v92, v93
	v_lshlrev_b32_e32 v92, 16, v98
	v_and_b32_e32 v93, 0xffff0000, v98
	v_lshlrev_b32_e32 v94, 16, v226
	v_and_b32_e32 v95, 0xffff0000, v226
	v_mul_f32_e32 v92, v92, v94
	v_mul_f32_e32 v93, v93, v95
	v_cvt_pk_bf16_f32 v66, v92, v93
	v_lshlrev_b32_e32 v92, 16, v99
	v_and_b32_e32 v93, 0xffff0000, v99
	v_lshlrev_b32_e32 v94, 16, v227
	v_and_b32_e32 v95, 0xffff0000, v227
	v_mul_f32_e32 v92, v92, v94
	v_mul_f32_e32 v93, v93, v95
	v_cvt_pk_bf16_f32 v67, v92, v93
	global_store_dwordx4 v[240:241], v[64:67], off
	s_waitcnt lgkmcnt(2)
	v_lshlrev_b32_e32 v92, 16, v100
	v_and_b32_e32 v93, 0xffff0000, v100
	v_lshlrev_b32_e32 v94, 16, v228
	v_and_b32_e32 v95, 0xffff0000, v228
	v_mul_f32_e32 v92, v92, v94
	v_mul_f32_e32 v93, v93, v95
	v_cvt_pk_bf16_f32 v68, v92, v93
	v_lshlrev_b32_e32 v92, 16, v101
	v_and_b32_e32 v93, 0xffff0000, v101
	v_lshlrev_b32_e32 v94, 16, v229
	v_and_b32_e32 v95, 0xffff0000, v229
	v_mul_f32_e32 v92, v92, v94
	v_mul_f32_e32 v93, v93, v95
	v_cvt_pk_bf16_f32 v69, v92, v93
	v_lshlrev_b32_e32 v92, 16, v102
	v_and_b32_e32 v93, 0xffff0000, v102
	v_lshlrev_b32_e32 v94, 16, v230
	v_and_b32_e32 v95, 0xffff0000, v230
	v_mul_f32_e32 v92, v92, v94
	v_mul_f32_e32 v93, v93, v95
	v_cvt_pk_bf16_f32 v70, v92, v93
	v_lshlrev_b32_e32 v92, 16, v103
	v_and_b32_e32 v93, 0xffff0000, v103
	v_lshlrev_b32_e32 v94, 16, v231
	v_and_b32_e32 v95, 0xffff0000, v231
	v_mul_f32_e32 v92, v92, v94
	v_mul_f32_e32 v93, v93, v95
	v_cvt_pk_bf16_f32 v71, v92, v93
	global_store_dwordx4 v[242:243], v[68:71], off
	s_waitcnt lgkmcnt(1)
	v_lshlrev_b32_e32 v92, 16, v104
	v_and_b32_e32 v93, 0xffff0000, v104
	v_lshlrev_b32_e32 v94, 16, v232
	v_and_b32_e32 v95, 0xffff0000, v232
	v_mul_f32_e32 v92, v92, v94
	v_mul_f32_e32 v93, v93, v95
	v_cvt_pk_bf16_f32 v72, v92, v93
	v_lshlrev_b32_e32 v92, 16, v105
	v_and_b32_e32 v93, 0xffff0000, v105
	v_lshlrev_b32_e32 v94, 16, v233
	v_and_b32_e32 v95, 0xffff0000, v233
	v_mul_f32_e32 v92, v92, v94
	v_mul_f32_e32 v93, v93, v95
	v_cvt_pk_bf16_f32 v73, v92, v93
	v_lshlrev_b32_e32 v92, 16, v106
	v_and_b32_e32 v93, 0xffff0000, v106
	v_lshlrev_b32_e32 v94, 16, v234
	v_and_b32_e32 v95, 0xffff0000, v234
	v_mul_f32_e32 v92, v92, v94
	v_mul_f32_e32 v93, v93, v95
	v_cvt_pk_bf16_f32 v74, v92, v93
	v_lshlrev_b32_e32 v92, 16, v107
	v_and_b32_e32 v93, 0xffff0000, v107
	v_lshlrev_b32_e32 v94, 16, v235
	v_and_b32_e32 v95, 0xffff0000, v235
	v_mul_f32_e32 v92, v92, v94
	v_mul_f32_e32 v93, v93, v95
	v_cvt_pk_bf16_f32 v75, v92, v93
	global_store_dwordx4 v[244:245], v[72:75], off
	s_waitcnt lgkmcnt(0)
	v_lshlrev_b32_e32 v92, 16, v108
	v_and_b32_e32 v93, 0xffff0000, v108
	v_lshlrev_b32_e32 v94, 16, v236
	v_and_b32_e32 v95, 0xffff0000, v236
	v_mul_f32_e32 v92, v92, v94
	v_mul_f32_e32 v93, v93, v95
	v_cvt_pk_bf16_f32 v76, v92, v93
	v_lshlrev_b32_e32 v92, 16, v109
	v_and_b32_e32 v93, 0xffff0000, v109
	v_lshlrev_b32_e32 v94, 16, v237
	v_and_b32_e32 v95, 0xffff0000, v237
	v_mul_f32_e32 v92, v92, v94
	v_mul_f32_e32 v93, v93, v95
	v_cvt_pk_bf16_f32 v77, v92, v93
	v_lshlrev_b32_e32 v92, 16, v110
	v_and_b32_e32 v93, 0xffff0000, v110
	v_lshlrev_b32_e32 v94, 16, v238
	v_and_b32_e32 v95, 0xffff0000, v238
	v_mul_f32_e32 v92, v92, v94
	v_mul_f32_e32 v93, v93, v95
	v_cvt_pk_bf16_f32 v78, v92, v93
	v_lshlrev_b32_e32 v92, 16, v111
	v_and_b32_e32 v93, 0xffff0000, v111
	v_lshlrev_b32_e32 v94, 16, v239
	v_and_b32_e32 v95, 0xffff0000, v239
	v_mul_f32_e32 v92, v92, v94
	v_mul_f32_e32 v93, v93, v95
	v_cvt_pk_bf16_f32 v79, v92, v93
	global_store_dwordx4 v[222:223], v[76:79], off
	s_branch .LBB0_829
